# M-phase: batched pool-window loads (W=16 prompt+sample), batched h0 loads, batched look-back loads, copy-out moved to WGs 64-127
# speedup vs baseline: 1.0193x; 1.0193x over previous
.LBB0_145:
	v_writelane_b32 v252, s56, 34
	s_nop 1
	v_writelane_b32 v252, s57, 35
	s_or_b64 exec, exec, s[0:1]
	s_add_u32 s80, s10, 0xec00000
	s_addc_u32 s81, s11, 0
	s_add_u32 s25, s10, 0x3800000
	s_addc_u32 s26, s11, 0
	s_add_u32 s0, s10, 0x5a00000
	s_addc_u32 s1, s11, 0
	s_add_u32 s4, s10, 0x400000
	v_writelane_b32 v252, s4, 36
	s_addc_u32 s4, s11, 0
	s_cmpk_lt_i32 s2, 0x400
	v_writelane_b32 v252, s4, 37
	s_cselect_b64 s[4:5], -1, 0
	v_writelane_b32 v252, s4, 38
	s_ashr_i32 s33, s2, 31
	s_ashr_i32 s13, s96, 31
	v_writelane_b32 v252, s5, 39
	s_lshr_b32 s4, s33, 29
	s_add_i32 s5, s2, s4
	s_ashr_i32 s4, s5, 3
	s_and_b32 s5, s5, -8
	s_sub_i32 s6, s2, s5
	s_lshl_b32 s7, s6, 7
	s_and_b32 s5, s1, 0xffff
	s_add_u32 s14, s10, 0xf000200
	s_addc_u32 s15, s11, 0
	s_add_u32 s62, s10, 0xf000400
	s_addc_u32 s63, s11, 0
	s_add_u32 s28, s10, 0xf000500
	v_writelane_b32 v252, s14, 40
	s_addc_u32 s29, s11, 0
	v_lshl_add_u64 v[0:1], v[0:1], 2, s[52:53]
	v_writelane_b32 v252, s15, 41
	s_add_u32 s14, s10, 0xf000600
	s_addc_u32 s15, s11, 0
	v_writelane_b32 v252, s14, 42
	s_mov_b32 s69, 0
	s_mul_i32 s97, s97, s96
	v_writelane_b32 v252, s15, 43
	s_add_u32 s14, s10, 0xf000700
	s_addc_u32 s15, s11, 0
	v_writelane_b32 v252, s14, 44
	s_mul_i32 s97, s97, s54
	s_mov_b32 s83, 0x20000
	v_writelane_b32 v252, s15, 45
	s_add_u32 s14, s10, 0xf000800
	s_addc_u32 s15, s11, 0
	v_writelane_b32 v252, s14, 46
	s_mov_b32 s82, 0x7ffffff0
	v_mov_b32_e32 v161, 0
	v_writelane_b32 v252, s15, 47
	s_add_u32 s14, s10, 0xf000900
	s_addc_u32 s15, s11, 0
	v_writelane_b32 v252, s14, 48
	v_mov_b32_e32 v228, 1
	v_mov_b32_e32 v229, 0x358637bd
	v_writelane_b32 v252, s15, 49
	s_add_u32 s14, s10, 0xf000a00
	s_addc_u32 s15, s11, 0
	v_writelane_b32 v252, s14, 50
	v_mov_b32_e32 v230, 0xec00000
	v_mov_b32_e32 v231, 0xc0
	v_writelane_b32 v252, s15, 51
	s_add_u32 s14, s10, 0xf000b00
	s_addc_u32 s15, s11, 0
	v_writelane_b32 v252, s14, 52
	s_mov_b64 s[76:77], 0x80
	s_nop 0
	v_writelane_b32 v252, s15, 53
	s_add_u32 s14, s10, 0xf000c00
	s_addc_u32 s15, s11, 0
	v_writelane_b32 v252, s14, 54
	s_barrier
	s_nop 0
	v_writelane_b32 v252, s15, 55
	s_add_u32 s14, s10, 0xf000d00
	s_addc_u32 s15, s11, 0
	v_writelane_b32 v252, s14, 56
	s_nop 1
	v_writelane_b32 v252, s15, 57
	s_add_u32 s14, s10, 0xf000e00
	s_addc_u32 s15, s11, 0
	v_writelane_b32 v252, s14, 58
	s_nop 1
	v_writelane_b32 v252, s15, 59
	s_add_u32 s14, s10, 0xf000f00
	s_addc_u32 s15, s11, 0
	v_writelane_b32 v252, s14, 60
	s_nop 1
	v_writelane_b32 v252, s15, 61
	s_add_u32 s14, s10, 0xf001000
	s_addc_u32 s15, s11, 0
	s_add_u32 s86, s10, 0xf001100
	s_addc_u32 s87, s11, 0
	s_add_u32 s74, s10, 0xf001200
	s_addc_u32 s75, s11, 0
	s_add_u32 s78, s10, 0xf001300
	s_addc_u32 s79, s11, 0
	v_writelane_b32 v252, s14, 62
	s_cmp_eq_u32 s12, 15
	s_nop 0
	v_writelane_b32 v252, s15, 63
	s_cselect_b64 s[14:15], -1, 0
	v_writelane_b32 v253, s14, 0
	s_cmp_eq_u32 s12, 14
	s_nop 0
	v_writelane_b32 v253, s15, 1
	s_cselect_b64 s[14:15], -1, 0
	v_writelane_b32 v253, s14, 2
	s_cmp_eq_u32 s12, 13
	s_nop 0
	v_writelane_b32 v253, s15, 3
	s_cselect_b64 s[14:15], -1, 0
	v_writelane_b32 v253, s14, 4
	s_cmp_eq_u32 s12, 12
	s_nop 0
	v_writelane_b32 v253, s15, 5
	s_cselect_b64 s[14:15], -1, 0
	v_writelane_b32 v253, s14, 6
	s_cmp_eq_u32 s12, 11
	s_nop 0
	v_writelane_b32 v253, s15, 7
	s_cselect_b64 s[14:15], -1, 0
	v_writelane_b32 v253, s14, 8
	s_cmp_eq_u32 s12, 10
	s_nop 0
	v_writelane_b32 v253, s15, 9
	s_cselect_b64 s[14:15], -1, 0
	v_writelane_b32 v253, s14, 10
	s_cmp_eq_u32 s12, 9
	s_nop 0
	v_writelane_b32 v253, s15, 11
	s_cselect_b64 s[14:15], -1, 0
	v_writelane_b32 v253, s14, 12
	s_cmp_eq_u32 s12, 8
	s_nop 0
	v_writelane_b32 v253, s15, 13
	s_cselect_b64 s[14:15], -1, 0
	v_writelane_b32 v253, s14, 14
	s_cmp_eq_u32 s12, 7
	s_nop 0
	v_writelane_b32 v253, s15, 15
	s_mov_b64 s[14:15], 0x1400
	v_lshl_add_u64 v[218:219], v[0:1], 0, s[14:15]
	s_mov_b64 s[14:15], 0x2400
	v_lshl_add_u64 v[220:221], v[0:1], 0, s[14:15]
	s_cselect_b64 s[14:15], -1, 0
	v_writelane_b32 v253, s14, 16
	s_cmp_eq_u32 s12, 6
	s_nop 0
	v_writelane_b32 v253, s15, 17
	s_cselect_b64 s[14:15], -1, 0
	v_writelane_b32 v253, s14, 18
	s_cmp_eq_u32 s12, 5
	s_nop 0
	v_writelane_b32 v253, s15, 19
	s_cselect_b64 s[14:15], -1, 0
	v_writelane_b32 v253, s14, 20
	s_cmp_eq_u32 s12, 4
	s_nop 0
	v_writelane_b32 v253, s15, 21
	s_cselect_b64 s[14:15], -1, 0
	v_writelane_b32 v253, s14, 22
	s_cmp_eq_u32 s12, 3
	s_nop 0
	v_writelane_b32 v253, s15, 23
	s_cselect_b64 s[14:15], -1, 0
	v_writelane_b32 v253, s14, 24
	s_cmp_eq_u32 s12, 2
	s_nop 0
	v_writelane_b32 v253, s15, 25
	s_cselect_b64 s[14:15], -1, 0
	v_writelane_b32 v253, s14, 26
	s_cmp_eq_u32 s12, 1
	s_nop 0
	v_writelane_b32 v253, s15, 27
	s_cselect_b64 s[14:15], -1, 0
	v_writelane_b32 v253, s14, 28
	s_cmp_eq_u32 s12, 0
	s_nop 0
	v_writelane_b32 v253, s15, 29
	s_cselect_b64 s[14:15], -1, 0
	v_writelane_b32 v253, s14, 30
	s_nop 1
	v_writelane_b32 v253, s15, 31
	s_add_u32 s14, s10, 0xf003400
	s_addc_u32 s15, s11, 0
	v_writelane_b32 v253, s14, 32
	s_nop 1
	v_writelane_b32 v253, s15, 33
	s_add_u32 s14, s10, 0xf003500
	s_addc_u32 s15, s11, 0
	v_writelane_b32 v253, s14, 34
	s_add_u32 s12, s10, 0xef00000
	s_nop 0
	v_writelane_b32 v253, s15, 35
	v_writelane_b32 v253, s12, 36
	s_addc_u32 s12, s11, 0
	s_cmp_gt_i32 s2, 63
	v_writelane_b32 v253, s12, 37
	s_cselect_b64 s[14:15], -1, 0
	v_writelane_b32 v253, s14, 38
	s_add_i32 s12, s2, 0xffffff80
	s_nop 0
	v_writelane_b32 v253, s15, 39
	v_writelane_b32 v253, s12, 40
	s_sub_i32 s14, s2, 64
	s_add_i32 s12, s2, 0x80
	s_cmp_lt_u32 s55, 64
	v_writelane_b32 v253, s12, 41
	s_cselect_b64 s[16:17], -1, 0
	v_writelane_b32 v253, s16, 42
	v_readlane_b32 s12, v252, 32
	s_lshl_b32 s15, s12, 4
	v_writelane_b32 v253, s17, 43
	s_lshl_b32 s34, s12, 5
	s_add_i32 s12, s3, 0x1000
	v_writelane_b32 v253, s15, 44
	s_add_u32 s16, s10, 0x3600000
	v_writelane_b32 v253, s12, 45
	s_addc_u32 s17, s11, 0
	v_writelane_b32 v253, s16, 46
	s_nop 1
	v_writelane_b32 v253, s17, 47
	s_add_u32 s16, s10, 0x3700000
	s_addc_u32 s17, s11, 0
	v_writelane_b32 v253, s16, 48
	s_nop 1
	v_writelane_b32 v253, s17, 49
	s_add_u32 s16, s10, 0x3400000
	s_addc_u32 s17, s11, 0
	v_writelane_b32 v253, s16, 50
	s_add_u32 s12, s10, 0x5800000
	s_nop 0
	v_writelane_b32 v253, s17, 51
	v_writelane_b32 v253, s12, 52
	s_addc_u32 s12, s11, 0
	s_add_u32 s88, s10, 0xda00000
	s_addc_u32 s20, s11, 0
	s_add_u32 s16, s10, 0xec10000
	v_writelane_b32 v253, s12, 53
	s_addc_u32 s17, s11, 0
	v_writelane_b32 v253, s16, 54
	s_and_b32 s89, s20, 0xffff
	v_writelane_b32 v253, s17, 55
	s_nop 1
	v_writelane_b32 v253, s14, 56
	s_sub_i32 s12, s2, 0x80
	s_cmpk_lt_u32 s12, 0x60
	s_cselect_b64 s[14:15], -1, 0
	s_cmpk_lt_u32 s2, 0x40
	s_cselect_b64 s[16:17], -1, 0
	s_or_b64 s[14:15], s[14:15], s[16:17]
	s_add_i32 s12, s2, 0xffffff60
	s_add_i32 s16, s2, 0xffffffc0
	s_cmpk_lt_u32 s2, 0x80
	s_cselect_b32 s12, s16, s12
	s_nop 1
	v_writelane_b32 v253, s14, 57
	s_nop 1
	v_writelane_b32 v253, s15, 58
	s_nop 1
	v_writelane_b32 v253, s12, 59
	s_add_u32 s14, s8, 0x6460000
	s_addc_u32 s15, s9, 0
	v_writelane_b32 v253, s14, 60
	s_nop 1
	v_writelane_b32 v253, s15, 61
	s_add_u32 s14, s8, 0x4660000
	s_addc_u32 s15, s9, 0
	v_writelane_b32 v253, s14, 62
	s_nop 1
	v_writelane_b32 v253, s15, 63
	s_add_u32 s14, s8, 0x45e0000
	s_addc_u32 s15, s9, 0
	v_writelane_b32 v254, s14, 0
	s_nop 1
	v_writelane_b32 v254, s15, 1
	s_add_u32 s14, s8, 0x4400000
	s_addc_u32 s15, s9, 0
	s_add_u32 s35, s10, 0x5a01000
	v_writelane_b32 v254, s14, 2
	s_addc_u32 s36, s11, 0
	s_add_u32 s12, s10, 0x2400000
	v_writelane_b32 v254, s15, 3
	v_writelane_b32 v254, s12, 4
	s_addc_u32 s12, s11, 0
	s_cmpk_lt_i32 s2, 0x100
	v_writelane_b32 v254, s12, 5
	s_cselect_b64 s[14:15], -1, 0
	s_lshl_b32 s12, s6, 5
	s_add_u32 s19, s10, 0xda01000
	s_addc_u32 s21, s11, 0
	s_add_u32 s22, s10, 0xe400000
	s_addc_u32 s23, s11, 0
	v_writelane_b32 v254, s14, 6
	s_cmp_lt_i32 s2, 16
	s_nop 0
	v_writelane_b32 v254, s15, 7
	s_cselect_b64 s[14:15], -1, 0
	v_writelane_b32 v254, s14, 8
	s_lshl_b32 s38, s96, 4
	s_lshl_b32 s18, s6, 1
	v_writelane_b32 v254, s15, 9
	s_lshr_b32 s14, s33, 28
	s_add_i32 s16, s2, s14
	s_ashr_i32 s17, s16, 4
	s_lshl_b32 s14, s17, 9
	s_ashr_i32 s15, s14, 31
	v_writelane_b32 v254, s19, 10
	s_lshl_b64 s[14:15], s[14:15], 1
	s_add_i32 s40, s38, 0xfffffc00
	v_writelane_b32 v254, s21, 11
	s_add_u32 s37, s19, s14
	v_writelane_b32 v254, s14, 12
	s_addc_u32 s39, s21, s15
	s_add_i32 s68, s17, -2
	v_writelane_b32 v254, s15, 13
	s_and_b32 s14, s16, -16
	s_sub_i32 s24, s2, s14
	s_lshl_b64 s[14:15], s[68:69], 21
	s_add_u32 s16, s22, s14
	v_writelane_b32 v254, s22, 14
	s_addc_u32 s17, s23, s15
	s_add_i32 s14, s2, 15
	s_cmp_lt_u32 s14, 31
	s_cselect_b32 s14, 0, 0x800
	v_writelane_b32 v254, s23, 15
	s_add_u32 s19, s88, s14
	v_writelane_b32 v254, s20, 16
	s_addc_u32 s20, s20, 0
	s_bfe_i32 s14, s24, 0x80000
	s_bfe_u32 s14, s14, 0x3000c
	s_add_i32 s14, s24, s14
	s_bfe_i32 s15, s14, 0x80000
	s_and_b32 s14, s14, 0xfff8
	s_sext_i32_i16 s15, s15
	s_sub_i32 s14, s24, s14
	s_ashr_i32 s15, s15, 3
	s_bfe_i32 s21, s14, 0x80000
	s_lshl_b32 s22, s14, 1
	v_writelane_b32 v254, s24, 17
	s_ashr_i32 s23, s24, 31
	v_writelane_b32 v254, s23, 18
	s_cmp_lt_i32 s6, 0
	s_mul_i32 s23, s6, 0x81
	s_cselect_b32 s7, s23, s7
	s_mul_i32 s23, s6, 33
	s_mul_i32 s6, s6, 3
	s_cselect_b32 s12, s23, s12
	s_cselect_b32 s18, s6, s18
	s_add_i32 s6, s7, s4
	s_ashr_i32 s7, s6, 31
	s_lshr_b32 s7, s7, 25
	s_add_i32 s7, s6, s7
	s_and_b32 s23, s7, 0xff80
	s_sub_i32 s6, s6, s23
	s_bfe_i32 s23, s6, 0x80000
	s_bfe_u32 s23, s23, 0x3000c
	s_add_i32 s23, s6, s23
	s_and_b32 s24, s23, 0xf8
	s_sub_i32 s6, s6, s24
	s_ashr_i32 s7, s7, 7
	s_bfe_i32 s23, s23, 0x80000
	s_lshl_b32 s7, s7, 3
	s_sext_i32_i16 s23, s23
	s_sext_i32_i8 s6, s6
	s_add_i32 s42, s7, s6
	s_ashr_i32 s6, s23, 3
	v_writelane_b32 v254, s6, 19
	s_lshr_b32 s6, s23, 3
	s_bfe_i64 s[6:7], s[6:7], 0x100000
	s_lshl_b64 s[6:7], s[6:7], 19
	v_writelane_b32 v254, s6, 20
	s_ashr_i32 s43, s42, 31
	s_mul_i32 s14, s14, 3
	v_writelane_b32 v254, s7, 21
	s_mov_b32 s6, s42
	v_writelane_b32 v254, s6, 22
	s_nop 1
	v_writelane_b32 v254, s7, 23
	s_lshl_b64 s[6:7], s[42:43], 19
	v_writelane_b32 v254, s25, 24
	s_add_u32 s6, s25, s6
	v_writelane_b32 v254, s26, 25
	s_addc_u32 s7, s26, s7
	s_add_u32 s24, s6, 0x40000
	v_writelane_b32 v254, s6, 26
	s_addc_u32 s25, s7, 0
	s_mov_b64 s[26:27], s[28:29]
	v_writelane_b32 v254, s7, 27
	s_add_i32 s6, s12, s4
	s_ashr_i32 s7, s6, 31
	s_lshr_b32 s7, s7, 27
	s_add_i32 s7, s6, s7
	s_and_b32 s12, s7, 0xffe0
	s_sub_i32 s6, s6, s12
	s_bfe_i32 s12, s6, 0x80000
	s_bfe_u32 s12, s12, 0x3000c
	s_add_i32 s12, s6, s12
	s_and_b32 s23, s12, 0xf8
	s_sub_i32 s6, s6, s23
	s_ashr_i32 s7, s7, 5
	s_bfe_i32 s12, s12, 0x80000
	v_writelane_b32 v254, s24, 28
	s_lshl_b32 s7, s7, 3
	s_sext_i32_i16 s12, s12
	s_sext_i32_i8 s6, s6
	v_writelane_b32 v254, s25, 29
	s_add_i32 s24, s7, s6
	s_ashr_i32 s6, s12, 3
	v_writelane_b32 v254, s6, 30
	s_lshr_b32 s6, s12, 3
	s_bfe_i64 s[6:7], s[6:7], 0x100000
	s_lshl_b64 s[6:7], s[6:7], 20
	v_writelane_b32 v254, s6, 31
	s_ashr_i32 s25, s24, 31
	s_mov_b32 s28, s69
	v_writelane_b32 v254, s7, 32
	s_mov_b32 s6, s24
	v_writelane_b32 v254, s6, 33
	s_nop 1
	v_writelane_b32 v254, s7, 34
	s_lshl_b64 s[6:7], s[24:25], 21
	s_add_u32 s6, s35, s6
	v_writelane_b32 v254, s35, 35
	s_addc_u32 s7, s36, s7
	v_writelane_b32 v254, s36, 36
	s_add_u32 s24, s6, 0x100000
	v_writelane_b32 v254, s6, 37
	s_addc_u32 s25, s7, 0
	s_add_i32 s4, s18, s4
	v_writelane_b32 v254, s7, 38
	s_ashr_i32 s6, s4, 31
	s_lshr_b32 s6, s6, 27
	s_add_i32 s6, s4, s6
	s_and_b32 s7, s6, 0xffffffe0
	s_ashr_i32 s6, s6, 5
	s_sub_i32 s23, s4, s7
	s_sext_i32_i16 s4, s21
	s_lshl_b32 s21, s6, 3
	v_writelane_b32 v254, s24, 39
	s_sub_i32 s6, 4, s21
	v_cvt_f32_i32_e32 v0, s23
	v_writelane_b32 v254, s25, 40
	s_min_u32 s24, s6, 8
	s_cmp_lt_i32 s4, 0
	s_cselect_b32 s4, s14, s22
	s_add_i32 s4, s4, s15
	s_bfe_i32 s6, s4, 0x80000
	s_bfe_u32 s6, s6, 0x2000d
	s_add_i32 s6, s4, s6
	s_bfe_i32 s7, s6, 0x80000
	s_sext_i32_i16 s12, s7
	s_and_b32 s6, s6, 0xfffc
	s_ashr_i32 s14, s12, 2
	s_lshr_b32 s12, s12, 2
	s_sub_i32 s4, s4, s6
	v_writelane_b32 v254, s14, 41
	s_bfe_i64 s[14:15], s[12:13], 0x100000
	s_bfe_i64 s[6:7], s[4:5], 0x80000
	s_lshl_b64 s[14:15], s[14:15], 20
	s_lshl_b64 s[6:7], s[6:7], 21
	v_writelane_b32 v254, s14, 42
	s_add_u32 s6, s37, s6
	s_addc_u32 s7, s39, s7
	v_writelane_b32 v254, s15, 43
	v_writelane_b32 v254, s37, 44
	v_writelane_b32 v254, s39, 45
	s_add_u32 s14, s6, 0x100000
	v_cvt_f32_ubyte0_e32 v1, s24
	v_writelane_b32 v254, s6, 46
	s_addc_u32 s15, s7, 0
	v_rcp_iflag_f32_e32 v2, v1
	s_cmp_lt_i32 s2, 32
	v_writelane_b32 v254, s7, 47
	s_cselect_b32 s6, s20, s17
	s_movk_i32 s7, 0x1000
	v_writelane_b32 v254, s14, 48
	s_cselect_b32 s12, s7, 0x400
	s_cselect_b32 s18, 13, 11
	s_cselect_b32 s92, s19, s16
	s_and_b32 s93, s6, 0xffff
	s_ashr_i32 s6, s23, 30
	v_writelane_b32 v254, s15, 49
	s_or_b32 s14, s6, 1
	v_mul_f32_e32 v2, v0, v2
	s_lshl_b32 s6, s12, 5
	v_trunc_f32_e32 v2, v2
	v_writelane_b32 v254, s6, 50
	v_fma_f32 v0, -v2, v1, v0
	v_writelane_b32 v254, s34, 51
	s_add_i32 s6, s34, 0
	v_writelane_b32 v254, s6, 52
	v_cmp_ge_f32_e64 s[6:7], |v0|, v1
	v_cvt_i32_f32_e32 v0, v2
	s_and_b64 s[6:7], s[6:7], exec
	s_sext_i32_i8 s4, s4
	v_writelane_b32 v254, s4, 53
	s_cselect_b32 s4, s14, 0
	v_readfirstlane_b32 s6, v0
	s_add_i32 s6, s6, s4
	s_mul_i32 s4, s6, s24
	s_sub_i32 s7, s23, s4
	s_sext_i32_i8 s7, s7
	s_add_i32 s14, s21, s7
	s_sext_i32_i8 s7, s6
	v_writelane_b32 v254, s7, 54
	s_bfe_i64 s[6:7], s[6:7], 0x80000
	s_lshl_b64 s[6:7], s[6:7], 20
	v_writelane_b32 v254, s6, 55
	s_ashr_i32 s15, s14, 31
	s_mov_b32 s4, s0
	v_writelane_b32 v254, s7, 56
	s_mul_i32 s6, s12, 0xc0
	v_writelane_b32 v254, s6, 57
	s_mov_b32 s6, s14
	v_writelane_b32 v254, s6, 58
	s_mov_b32 s12, 0xbfb8aa3b
	s_nop 0
	v_writelane_b32 v254, s7, 59
	s_lshl_b64 s[6:7], s[14:15], 21
	v_writelane_b32 v254, s6, 60
	s_mov_b64 s[14:15], 0xffffffff
	s_nop 0
	v_writelane_b32 v254, s7, 61
	s_add_u32 s6, s10, 0x5840080
	v_writelane_b32 v254, s6, 62
	s_addc_u32 s6, s11, 0
	v_writelane_b32 v254, s6, 63
	s_add_u32 s6, s10, 0x400100
	v_writelane_b32 v255, s6, 0
	s_addc_u32 s6, s11, 0
	s_ashr_i32 s39, s38, 31
	v_writelane_b32 v255, s6, 1
	s_add_i32 s6, s3, 0xfffbf800
	s_lshl_b64 s[70:71], s[38:39], 2
	v_writelane_b32 v255, s6, 2
	s_add_u32 s6, s8, 0x1000
	v_writelane_b32 v255, s6, 3
	s_addc_u32 s6, s9, 0
	v_writelane_b32 v255, s6, 4
	s_lshl_b32 s6, s2, 4
	s_addk_i32 s6, 0x3c00
	v_writelane_b32 v255, s6, 5
	s_add_i32 s6, 0, 0x20004
	v_writelane_b32 v255, s6, 6
	s_lshl_b64 s[6:7], s[38:39], 12
	v_writelane_b32 v255, s6, 7
	s_ashr_i32 s41, s40, 31
	s_lshl_b64 s[84:85], s[38:39], 11
	v_writelane_b32 v255, s7, 8
	s_mov_b32 s6, s38
	v_writelane_b32 v255, s6, 9
	s_nop 1
	v_writelane_b32 v255, s7, 10
	s_lshl_b64 s[6:7], s[38:39], 13
	v_writelane_b32 v255, s6, 11
	s_nop 1
	v_writelane_b32 v255, s7, 12
	s_lshl_b64 s[6:7], s[40:41], 2
	v_writelane_b32 v255, s6, 13
	s_nop 1
	v_writelane_b32 v255, s7, 14
	s_lshl_b64 s[6:7], s[40:41], 12
	v_writelane_b32 v255, s6, 15
	s_nop 1
	v_writelane_b32 v255, s7, 16
	s_lshl_b64 s[6:7], s[40:41], 11
	v_writelane_b32 v255, s6, 17
	s_nop 1
	v_writelane_b32 v255, s7, 18
	s_mov_b32 s6, s40
	v_writelane_b32 v255, s6, 19
	s_nop 1
	v_writelane_b32 v255, s7, 20
	s_lshl_b64 s[6:7], s[40:41], 13
	v_writelane_b32 v255, s6, 21
	s_nop 1
	v_writelane_b32 v255, s7, 22
	v_writelane_b32 v255, s62, 23
	s_nop 1
	v_writelane_b32 v255, s63, 24
	v_writelane_b32 v255, s26, 25
	s_nop 1
	v_writelane_b32 v255, s27, 26
	v_writelane_b32 v255, s80, 27
	s_nop 1
	v_writelane_b32 v255, s81, 28
	s_branch .LBB0_149

.LBB0_270:
	s_or_b64 exec, exec, s[16:17]
	s_waitcnt vmcnt(0)
	v_fma_f32 v71, v60, v72, v56
	v_fma_f32 v117, v61, v73, v57
	v_lshlrev_b32_e32 v72, 13, v111
	v_mov_b32_e32 v73, v161
	v_fma_f32 v116, v62, v74, v58
	v_fma_f32 v65, v63, v75, v59
	v_lshl_add_u64 v[72:73], v[112:113], 0, v[72:73]
	v_mov_b32_e32 v115, v161
	v_fmac_f32_e32 v116, v50, v90
	v_fmac_f32_e32 v65, v51, v91
	v_fma_f32 v109, v62, v90, v58
	v_fma_f32 v119, v63, v91, v59
	v_lshl_add_u64 v[90:91], v[72:73], 0, v[114:115]
	global_load_dwordx4 v[72:75], v[90:91], off offset:2048
	s_movk_i32 s16, 0x2000
	v_fma_f32 v107, v44, v84, v52
	v_mov_b32_e32 v84, v80
	v_mov_b32_e32 v80, v82
	v_mov_b32_e32 v82, v76
	v_add_co_u32_e32 v76, vcc, s16, v90
	v_fma_f32 v67, v45, v85, v53
	v_mov_b32_e32 v85, v32
	v_mov_b32_e32 v32, v81
	v_mov_b32_e32 v81, v34
	v_mov_b32_e32 v34, v83
	v_mov_b32_e32 v83, v36
	v_mov_b32_e32 v36, v77
	v_addc_co_u32_e32 v77, vcc, 0, v91, vcc
	v_fma_f32 v105, v46, v86, v54
	v_fma_f32 v121, v47, v87, v55
	v_mov_b32_e32 v86, v78
	v_mov_b32_e32 v87, v38
	v_mov_b32_e32 v38, v79
	global_load_dwordx4 v[76:79], v[76:77], off offset:2048
	v_fmac_f32_e32 v71, v48, v88
	v_fma_f32 v125, v60, v88, v56
	v_fmac_f32_e32 v107, v40, v92
	v_fmac_f32_e32 v67, v41, v93
	v_fma_f32 v120, v44, v92, v52
	v_fma_f32 v123, v45, v93, v53
	v_fmac_f32_e32 v121, v43, v95
	v_fma_f32 v122, v47, v95, v55
	v_fmac_f32_e32 v117, v49, v89
	v_fma_f32 v126, v61, v89, v57
	v_fmac_f32_e32 v125, v48, v68
	v_fmac_f32_e32 v126, v49, v110
	v_mov_b32_e32 v128, v62
	v_mov_b32_e32 v129, v50
	v_fmac_f32_e32 v109, v50, v70
	v_fmac_f32_e32 v119, v51, v108
	v_fmac_f32_e32 v120, v40, v64
	v_fmac_f32_e32 v123, v41, v106
	v_fmac_f32_e32 v105, v42, v94
	v_fma_f32 v124, v46, v94, v54
	v_mov_b32_e32 v130, v46
	v_mov_b32_e32 v131, v42
	v_fmac_f32_e32 v124, v42, v66
	v_fmac_f32_e32 v122, v43, v104
	s_movk_i32 s16, 0x4000
	v_and_b32_e32 v94, 0xffffffc, v118
	s_movk_i32 s27, 0x110
	v_readlane_b32 s44, v252, 0
	v_readlane_b32 s52, v252, 8
	v_readlane_b32 s53, v252, 9
	v_readlane_b32 s45, v252, 1
	v_readlane_b32 s46, v252, 2
	v_readlane_b32 s47, v252, 3
	v_readlane_b32 s48, v252, 4
	v_readlane_b32 s49, v252, 5
	v_readlane_b32 s50, v252, 6
	v_readlane_b32 s51, v252, 7
	v_readlane_b32 s54, v252, 10
	v_readlane_b32 s55, v252, 11
	v_readlane_b32 s56, v252, 12
	v_readlane_b32 s57, v252, 13
	v_readlane_b32 s58, v252, 14
	v_readlane_b32 s59, v252, 15
	s_waitcnt vmcnt(1)
	v_lshlrev_b32_e32 v88, 16, v72
	v_mov_b32_e32 v69, v88
	v_pk_mul_f32 v[92:93], v[84:85], v[68:69]
	s_waitcnt vmcnt(0)
	v_lshlrev_b32_e32 v89, 16, v76
	v_add_f32_e32 v71, v71, v92
	v_add_f32_e32 v95, v71, v93
	v_mov_b32_e32 v92, v60
	v_mov_b32_e32 v93, v48
	v_pk_mul_f32 v[68:69], v[92:93], v[68:69]
	v_pk_mul_f32 v[114:115], v[84:85], v[88:89]
	v_add_f32_e32 v48, v56, v68
	v_and_b32_e32 v68, 0xffff0000, v72
	v_add_f32_e32 v71, v125, v114
	v_mov_b32_e32 v111, v68
	v_add_f32_e32 v112, v71, v115
	v_pk_mul_f32 v[114:115], v[32:33], v[110:111]
	v_add_f32_e32 v113, v48, v69
	v_add_f32_e32 v48, v117, v114
	v_and_b32_e32 v69, 0xffff0000, v76
	v_add_f32_e32 v76, v48, v115
	v_mov_b32_e32 v48, v61
	v_pk_mul_f32 v[60:61], v[48:49], v[110:111]
	v_pk_mul_f32 v[114:115], v[32:33], v[68:69]
	v_add_f32_e32 v60, v57, v60
	v_add_f32_e32 v71, v126, v114
	v_add_f32_e32 v111, v60, v61
	v_lshlrev_b32_e32 v60, 16, v73
	v_add_f32_e32 v110, v71, v115
	v_mov_b32_e32 v71, v60
	v_lshlrev_b32_e32 v61, 16, v77
	v_pk_mul_f32 v[114:115], v[80:81], v[70:71]
	v_pk_mul_f32 v[70:71], v[128:129], v[70:71]
	v_add_f32_e32 v72, v116, v114
	v_pk_mul_f32 v[126:127], v[80:81], v[60:61]
	v_add_f32_e32 v50, v58, v70
	v_and_b32_e32 v70, 0xffff0000, v73
	v_add_f32_e32 v115, v72, v115
	v_add_f32_e32 v72, v109, v126
	v_mov_b32_e32 v109, v70
	v_add_f32_e32 v114, v72, v127
	v_pk_mul_f32 v[72:73], v[34:35], v[108:109]
	v_add_f32_e32 v117, v50, v71
	v_add_f32_e32 v50, v65, v72
	v_add_f32_e32 v116, v50, v73
	v_mov_b32_e32 v50, v63
	v_and_b32_e32 v71, 0xffff0000, v77
	v_pk_mul_f32 v[62:63], v[50:51], v[108:109]
	v_pk_mul_f32 v[72:73], v[34:35], v[70:71]
	v_add_f32_e32 v62, v59, v62
	v_add_f32_e32 v65, v119, v72
	v_add_f32_e32 v119, v62, v63
	v_lshlrev_b32_e32 v62, 16, v74
	v_add_f32_e32 v77, v65, v73
	v_mov_b32_e32 v65, v62
	v_pk_mul_f32 v[72:73], v[82:83], v[64:65]
	v_mov_b32_e32 v126, v44
	v_mov_b32_e32 v127, v40
	v_lshlrev_b32_e32 v63, 16, v78
	v_add_f32_e32 v72, v107, v72
	v_pk_mul_f32 v[64:65], v[126:127], v[64:65]
	v_add_f32_e32 v109, v72, v73
	v_pk_mul_f32 v[72:73], v[82:83], v[62:63]
	v_add_f32_e32 v40, v52, v64
	v_and_b32_e32 v64, 0xffff0000, v74
	v_add_f32_e32 v72, v120, v72
	v_mov_b32_e32 v107, v64
	v_add_f32_e32 v108, v72, v73
	v_pk_mul_f32 v[72:73], v[36:37], v[106:107]
	v_add_f32_e32 v120, v40, v65
	v_and_b32_e32 v65, 0xffff0000, v78
	v_add_f32_e32 v40, v67, v72
	v_add_f32_e32 v78, v40, v73
	v_pk_mul_f32 v[72:73], v[36:37], v[64:65]
	v_mov_b32_e32 v40, v45
	v_add_f32_e32 v67, v123, v72
	v_pk_mul_f32 v[44:45], v[40:41], v[106:107]
	v_lshlrev_b32_e32 v72, 16, v75
	v_add_f32_e32 v44, v53, v44
	v_add_f32_e32 v74, v67, v73
	v_mov_b32_e32 v67, v72
	v_add_f32_e32 v123, v44, v45
	v_pk_mul_f32 v[44:45], v[86:87], v[66:67]
	v_lshlrev_b32_e32 v73, 16, v79
	v_add_f32_e32 v44, v105, v44
	v_pk_mul_f32 v[66:67], v[130:131], v[66:67]
	v_add_f32_e32 v107, v44, v45
	v_pk_mul_f32 v[44:45], v[86:87], v[72:73]
	v_add_f32_e32 v42, v54, v66
	v_and_b32_e32 v66, 0xffff0000, v75
	v_add_f32_e32 v44, v124, v44
	v_mov_b32_e32 v105, v66
	v_add_f32_e32 v106, v44, v45
	v_pk_mul_f32 v[44:45], v[38:39], v[104:105]
	v_add_f32_e32 v124, v42, v67
	v_and_b32_e32 v67, 0xffff0000, v79
	v_add_f32_e32 v42, v121, v44
	v_add_f32_e32 v79, v42, v45
	v_pk_mul_f32 v[44:45], v[38:39], v[66:67]
	v_pk_mul_f32 v[40:41], v[40:41], v[64:65]
	v_add_f32_e32 v44, v122, v44
	v_add_f32_e32 v75, v44, v45
	v_pk_mul_f32 v[44:45], v[92:93], v[88:89]
	v_add_f32_e32 v40, v53, v40
	v_add_f32_e32 v44, v56, v44
	v_add_f32_e32 v56, v44, v45
	v_pk_mul_f32 v[44:45], v[48:49], v[68:69]
	v_mov_b32_e32 v42, v47
	v_add_f32_e32 v44, v57, v44
	v_add_f32_e32 v48, v44, v45
	v_pk_mul_f32 v[44:45], v[128:129], v[60:61]
	v_pk_mul_f32 v[46:47], v[42:43], v[104:105]
	v_add_f32_e32 v44, v58, v44
	v_add_f32_e32 v49, v44, v45
	v_pk_mul_f32 v[44:45], v[50:51], v[70:71]
	v_add_f32_e32 v46, v55, v46
	v_add_f32_e32 v44, v59, v44
	v_add_f32_e32 v50, v44, v45
	v_pk_mul_f32 v[44:45], v[126:127], v[62:63]
	v_add_f32_e32 v104, v46, v47
	v_add_f32_e32 v44, v52, v44
	v_add_f32_e32 v52, v40, v41
	v_pk_mul_f32 v[40:41], v[130:131], v[72:73]
	v_add_f32_e32 v51, v44, v45
	v_add_f32_e32 v40, v54, v40
	v_add_f32_e32 v53, v40, v41
	v_pk_mul_f32 v[40:41], v[42:43], v[66:67]
	v_lshl_add_u64 v[128:129], v[160:161], 2, s[52:53]
	v_add_f32_e32 v40, v55, v40
	v_add_f32_e32 v54, v40, v41
	v_add_co_u32_e32 v40, vcc, s16, v90
	s_movk_i32 s16, 0x6000
	s_nop 0
	v_addc_co_u32_e32 v41, vcc, 0, v91, vcc
	v_add_co_u32_e32 v44, vcc, s16, v90
	global_load_dwordx4 v[40:43], v[40:41], off offset:2048
	s_nop 0
	v_addc_co_u32_e32 v45, vcc, 0, v91, vcc
	global_load_dwordx4 v[44:47], v[44:45], off offset:2048
	s_waitcnt vmcnt(1)
	v_and_b32_e32 v58, 0xffff0000, v43
	s_waitcnt vmcnt(0)
	v_and_b32_e32 v59, 0xffff0000, v47
	v_pk_mov_b32 v[66:67], v[66:67], v[58:59] op_sel:[1,0]
	s_nop 0
	v_pk_mul_f32 v[66:67], v[38:39], v[66:67]
	v_pk_mul_f32 v[38:39], v[38:39], v[58:59]
	v_add_f32_e32 v55, v104, v66
	v_add_f32_e32 v38, v54, v38
	v_add_f32_e32 v58, v38, v39
	v_lshlrev_b32_e32 v38, 16, v43
	v_lshlrev_b32_e32 v39, 16, v47
	v_add_f32_e32 v57, v55, v67
	v_pk_mov_b32 v[54:55], v[72:73], v[38:39] op_sel:[1,0]
	v_pk_mul_f32 v[38:39], v[86:87], v[38:39]
	v_pk_mul_f32 v[54:55], v[86:87], v[54:55]
	v_add_f32_e32 v38, v53, v38
	v_add_f32_e32 v43, v124, v54
	v_add_f32_e32 v47, v38, v39
	v_and_b32_e32 v39, 0xffff0000, v46
	v_and_b32_e32 v38, 0xffff0000, v42
	v_add_f32_e32 v43, v43, v55
	v_pk_mov_b32 v[54:55], v[64:65], v[38:39] op_sel:[1,0]
	s_nop 0
	v_pk_mul_f32 v[54:55], v[36:37], v[54:55]
	v_pk_mul_f32 v[36:37], v[36:37], v[38:39]
	v_add_f32_e32 v53, v123, v54
	v_add_f32_e32 v36, v52, v36
	v_add_f32_e32 v52, v36, v37
	v_lshlrev_b32_e32 v36, 16, v42
	v_lshlrev_b32_e32 v37, 16, v46
	v_pk_mov_b32 v[38:39], v[62:63], v[36:37] op_sel:[1,0]
	v_pk_mul_f32 v[36:37], v[82:83], v[36:37]
	v_pk_mul_f32 v[38:39], v[82:83], v[38:39]
	v_add_f32_e32 v36, v51, v36
	v_add_f32_e32 v38, v120, v38
	v_add_f32_e32 v46, v36, v37
	v_and_b32_e32 v37, 0xffff0000, v45
	v_and_b32_e32 v36, 0xffff0000, v41
	v_add_f32_e32 v42, v38, v39
	v_pk_mov_b32 v[38:39], v[70:71], v[36:37] op_sel:[1,0]
	v_add_f32_e32 v53, v53, v55
	v_pk_mul_f32 v[38:39], v[34:35], v[38:39]
	v_pk_mul_f32 v[34:35], v[34:35], v[36:37]
	v_add_f32_e32 v38, v119, v38
	v_add_f32_e32 v34, v50, v34
	v_add_f32_e32 v50, v34, v35
	v_lshlrev_b32_e32 v34, 16, v41
	v_lshlrev_b32_e32 v35, 16, v45
	v_pk_mov_b32 v[36:37], v[60:61], v[34:35] op_sel:[1,0]
	v_pk_mul_f32 v[34:35], v[80:81], v[34:35]
	v_pk_mul_f32 v[36:37], v[80:81], v[36:37]
	v_add_f32_e32 v34, v49, v34
	v_add_f32_e32 v36, v117, v36
	v_add_f32_e32 v45, v34, v35
	v_and_b32_e32 v35, 0xffff0000, v44
	v_and_b32_e32 v34, 0xffff0000, v40
	v_add_f32_e32 v41, v36, v37
	v_pk_mov_b32 v[36:37], v[68:69], v[34:35] op_sel:[1,0]
	v_add_f32_e32 v51, v38, v39
	v_pk_mul_f32 v[36:37], v[32:33], v[36:37]
	v_pk_mul_f32 v[32:33], v[32:33], v[34:35]
	v_add_f32_e32 v36, v111, v36
	v_add_f32_e32 v32, v48, v32
	v_add_f32_e32 v48, v32, v33
	v_lshlrev_b32_e32 v32, 16, v40
	v_lshlrev_b32_e32 v33, 16, v44
	v_pk_mov_b32 v[34:35], v[88:89], v[32:33] op_sel:[1,0]
	v_pk_mul_f32 v[32:33], v[84:85], v[32:33]
	v_add_f32_e32 v37, v36, v37
	v_pk_mul_f32 v[34:35], v[84:85], v[34:35]
	v_add_f32_e32 v32, v56, v32
	v_lshl_add_u32 v36, v103, 1, 0
	v_add_f32_e32 v34, v113, v34
	v_add_f32_e32 v44, v32, v33
	v_cvt_pk_bf16_f32 v32, v95, v76
	v_cvt_pk_bf16_f32 v33, v115, v116
	v_mad_u64_u32 v[38:39], s[16:17], v94, s27, v[36:37]
	v_add_f32_e32 v40, v34, v35
	v_cvt_pk_bf16_f32 v34, v109, v78
	v_cvt_pk_bf16_f32 v35, v107, v79
	ds_write_b128 v38, v[32:35]
	v_cvt_pk_bf16_f32 v32, v112, v110
	v_cvt_pk_bf16_f32 v33, v114, v77
	v_cvt_pk_bf16_f32 v34, v108, v74
	v_cvt_pk_bf16_f32 v35, v106, v75
	ds_write_b128 v38, v[32:35] offset:272
	v_cvt_pk_bf16_f32 v32, v40, v37
	v_cvt_pk_bf16_f32 v33, v41, v51
	v_or_b32_e32 v37, 3, v118
	v_cvt_pk_bf16_f32 v34, v42, v53
	v_cvt_pk_bf16_f32 v35, v43, v57
	ds_write_b128 v38, v[32:35] offset:544
	v_cvt_pk_bf16_f32 v32, v44, v48
	v_cvt_pk_bf16_f32 v33, v45, v50
	v_mad_u64_u32 v[36:37], s[16:17], v37, s27, v[36:37]
	v_cvt_pk_bf16_f32 v34, v46, v52
	v_cvt_pk_bf16_f32 v35, v47, v58
	ds_write_b128 v36, v[32:35]
	v_lshlrev_b32_e32 v32, 1, v102
	v_mul_u32_u24_e32 v33, 0x110, v101
	v_add3_u32 v114, 0, v32, v33
	s_waitcnt lgkmcnt(0)
	s_barrier
	ds_read_b128 v[32:35], v114
	ds_read_b128 v[40:43], v114 offset:4352
	ds_read_b128 v[48:51], v114 offset:8704
	ds_read_b128 v[56:59], v114 offset:13056
	ds_read_b128 v[64:67], v114 offset:17408
	ds_read_b128 v[72:75], v114 offset:21760
	ds_read_b128 v[80:83], v114 offset:26112
	ds_read_b128 v[88:91], v114 offset:30464
	s_waitcnt lgkmcnt(7)
	v_mfma_f32_16x16x32_bf16 v[36:39], v[32:35], v[24:27], 0
	s_movk_i32 s16, 0x440
	v_mfma_f32_16x16x32_bf16 v[32:35], v[32:35], v[28:31], 0
	s_waitcnt lgkmcnt(6)
	v_mfma_f32_16x16x32_bf16 v[44:47], v[40:43], v[24:27], 0
	v_mfma_f32_16x16x32_bf16 v[40:43], v[40:43], v[28:31], 0
	s_waitcnt lgkmcnt(5)
	v_mfma_f32_16x16x32_bf16 v[52:55], v[48:51], v[24:27], 0
	v_mfma_f32_16x16x32_bf16 v[48:51], v[48:51], v[28:31], 0
	s_waitcnt lgkmcnt(4)
	v_mfma_f32_16x16x32_bf16 v[60:63], v[56:59], v[24:27], 0
	v_mfma_f32_16x16x32_bf16 v[56:59], v[56:59], v[28:31], 0
	s_waitcnt lgkmcnt(3)
	v_mfma_f32_16x16x32_bf16 v[68:71], v[64:67], v[24:27], 0
	v_mfma_f32_16x16x32_bf16 v[64:67], v[64:67], v[28:31], 0
	s_waitcnt lgkmcnt(2)
	v_mfma_f32_16x16x32_bf16 v[76:79], v[72:75], v[24:27], 0
	v_mfma_f32_16x16x32_bf16 v[72:75], v[72:75], v[28:31], 0
	s_waitcnt lgkmcnt(1)
	v_mfma_f32_16x16x32_bf16 v[84:87], v[80:83], v[24:27], 0
	v_mfma_f32_16x16x32_bf16 v[80:83], v[80:83], v[28:31], 0
	s_waitcnt lgkmcnt(0)
	v_mfma_f32_16x16x32_bf16 v[24:27], v[88:91], v[24:27], 0
	v_mfma_f32_16x16x32_bf16 v[28:31], v[88:91], v[28:31], 0
	ds_read_b128 v[88:91], v114 offset:64
	s_waitcnt lgkmcnt(0)
	v_mfma_f32_16x16x32_bf16 v[36:39], v[88:91], v[16:19], v[36:39]
	v_mfma_f32_16x16x32_bf16 v[32:35], v[88:91], v[20:23], v[32:35]
	ds_read_b128 v[88:91], v114 offset:4416
	s_waitcnt lgkmcnt(0)
	v_mfma_f32_16x16x32_bf16 v[44:47], v[88:91], v[16:19], v[44:47]
	v_mfma_f32_16x16x32_bf16 v[40:43], v[88:91], v[20:23], v[40:43]
	ds_read_b128 v[88:91], v114 offset:8768
	s_waitcnt lgkmcnt(0)
	v_mfma_f32_16x16x32_bf16 v[52:55], v[88:91], v[16:19], v[52:55]
	v_mfma_f32_16x16x32_bf16 v[48:51], v[88:91], v[20:23], v[48:51]
	ds_read_b128 v[88:91], v114 offset:13120
	s_waitcnt lgkmcnt(0)
	v_mfma_f32_16x16x32_bf16 v[60:63], v[88:91], v[16:19], v[60:63]
	v_mfma_f32_16x16x32_bf16 v[56:59], v[88:91], v[20:23], v[56:59]
	ds_read_b128 v[88:91], v114 offset:17472
	s_waitcnt lgkmcnt(0)
	v_mfma_f32_16x16x32_bf16 v[68:71], v[88:91], v[16:19], v[68:71]
	v_mfma_f32_16x16x32_bf16 v[64:67], v[88:91], v[20:23], v[64:67]
	ds_read_b128 v[88:91], v114 offset:21824
	s_waitcnt lgkmcnt(0)
	v_mfma_f32_16x16x32_bf16 v[76:79], v[88:91], v[16:19], v[76:79]
	v_mfma_f32_16x16x32_bf16 v[72:75], v[88:91], v[20:23], v[72:75]
	ds_read_b128 v[88:91], v114 offset:26176
	s_waitcnt lgkmcnt(0)
	v_mfma_f32_16x16x32_bf16 v[84:87], v[88:91], v[16:19], v[84:87]
	v_mfma_f32_16x16x32_bf16 v[80:83], v[88:91], v[20:23], v[80:83]
	ds_read_b128 v[88:91], v114 offset:30528
	s_waitcnt lgkmcnt(0)
	v_mfma_f32_16x16x32_bf16 v[16:19], v[88:91], v[16:19], v[24:27]
	s_nop 2
	ds_read_b128 v[24:27], v114 offset:128
	v_mfma_f32_16x16x32_bf16 v[20:23], v[88:91], v[20:23], v[28:31]
	s_waitcnt lgkmcnt(0)
	v_mfma_f32_16x16x32_bf16 v[28:31], v[24:27], v[8:11], v[36:39]
	v_mfma_f32_16x16x32_bf16 v[24:27], v[24:27], v[12:15], v[32:35]
	s_nop 2
	ds_read_b128 v[32:35], v114 offset:4480
	s_waitcnt lgkmcnt(0)
	v_mfma_f32_16x16x32_bf16 v[36:39], v[32:35], v[8:11], v[44:47]
	v_mfma_f32_16x16x32_bf16 v[32:35], v[32:35], v[12:15], v[40:43]
	s_nop 2
	ds_read_b128 v[40:43], v114 offset:8832
	s_waitcnt lgkmcnt(0)
	v_mfma_f32_16x16x32_bf16 v[44:47], v[40:43], v[8:11], v[52:55]
	v_mfma_f32_16x16x32_bf16 v[88:91], v[40:43], v[12:15], v[48:51]
	ds_read_b128 v[40:43], v114 offset:13184
	s_waitcnt lgkmcnt(0)
	v_mfma_f32_16x16x32_bf16 v[92:95], v[40:43], v[8:11], v[60:63]
	v_mfma_f32_16x16x32_bf16 v[102:105], v[40:43], v[12:15], v[56:59]
	ds_read_b128 v[40:43], v114 offset:17536
	s_waitcnt lgkmcnt(0)
	v_mfma_f32_16x16x32_bf16 v[68:71], v[40:43], v[8:11], v[68:71]
	v_mfma_f32_16x16x32_bf16 v[64:67], v[40:43], v[12:15], v[64:67]
	ds_read_b128 v[40:43], v114 offset:21888
	s_waitcnt lgkmcnt(0)
	v_mfma_f32_16x16x32_bf16 v[76:79], v[40:43], v[8:11], v[76:79]
	v_mfma_f32_16x16x32_bf16 v[72:75], v[40:43], v[12:15], v[72:75]
	ds_read_b128 v[40:43], v114 offset:26240
	s_waitcnt lgkmcnt(0)
	v_mfma_f32_16x16x32_bf16 v[84:87], v[40:43], v[8:11], v[84:87]
	v_mfma_f32_16x16x32_bf16 v[80:83], v[40:43], v[12:15], v[80:83]
	ds_read_b128 v[40:43], v114 offset:30592
	s_waitcnt lgkmcnt(0)
	v_mfma_f32_16x16x32_bf16 v[106:109], v[40:43], v[8:11], v[16:19]
	ds_read_b128 v[8:11], v114 offset:192
	v_mfma_f32_16x16x32_bf16 v[110:113], v[40:43], v[12:15], v[20:23]
	ds_read_b128 v[12:15], v114 offset:26304
	s_waitcnt lgkmcnt(1)
	v_mfma_f32_16x16x32_bf16 v[56:59], v[8:11], v[0:3], v[28:31]
	v_mfma_f32_16x16x32_bf16 v[60:63], v[8:11], v[4:7], v[24:27]
	ds_read_b128 v[8:11], v114 offset:4544
	s_nop 5
	v_pk_add_f32 v[56:57], v[98:99], v[56:57] op_sel_hi:[0,1]
	v_exp_f32_e32 v56, v56
	s_waitcnt lgkmcnt(0)
	v_mfma_f32_16x16x32_bf16 v[48:51], v[8:11], v[0:3], v[36:39]
	v_exp_f32_e32 v57, v57
	v_pk_add_f32 v[60:61], v[100:101], v[60:61] op_sel_hi:[0,1]
	v_exp_f32_e32 v60, v60
	v_mfma_f32_16x16x32_bf16 v[52:55], v[8:11], v[4:7], v[32:35]
	ds_read_b128 v[8:11], v114 offset:8896
	v_pk_add_f32 v[56:57], v[56:57], 1.0 op_sel_hi:[1,0]
	v_exp_f32_e32 v61, v61
	s_waitcnt lgkmcnt(0)
	v_mfma_f32_16x16x32_bf16 v[40:43], v[8:11], v[0:3], v[44:47]
	v_rcp_f32_e32 v56, v56
	v_rcp_f32_e32 v57, v57
	v_pk_add_f32 v[58:59], v[98:99], v[58:59] op_sel_hi:[0,1]
	v_mfma_f32_16x16x32_bf16 v[44:47], v[8:11], v[4:7], v[88:91]
	ds_read_b128 v[8:11], v114 offset:13248
	v_pk_mul_f32 v[56:57], v[96:97], v[56:57] op_sel_hi:[0,1]
	v_exp_f32_e32 v132, v56
	s_waitcnt lgkmcnt(0)
	v_mfma_f32_16x16x32_bf16 v[32:35], v[8:11], v[0:3], v[92:95]
	v_exp_f32_e32 v133, v57
	v_exp_f32_e32 v58, v58
	v_exp_f32_e32 v59, v59
	v_mfma_f32_16x16x32_bf16 v[36:39], v[8:11], v[4:7], v[102:105]
	ds_read_b128 v[8:11], v114 offset:17600
	v_pk_add_f32 v[60:61], v[60:61], 1.0 op_sel_hi:[1,0]
	v_pk_fma_f32 v[56:57], v[132:133], v[132:133], 1.0 op_sel_hi:[1,1,0] neg_lo:[1,0,0] neg_hi:[1,0,0]
	s_waitcnt lgkmcnt(0)
	v_mfma_f32_16x16x32_bf16 v[24:27], v[8:11], v[0:3], v[68:71]
	v_rcp_f32_e32 v60, v60
	v_rcp_f32_e32 v61, v61
	v_max_f32_e32 v56, 0x2b8cbccc, v56
	v_mfma_f32_16x16x32_bf16 v[28:31], v[8:11], v[4:7], v[64:67]
	ds_read_b128 v[8:11], v114 offset:21952
	v_max_f32_e32 v57, 0x2b8cbccc, v57
	v_pk_add_f32 v[58:59], v[58:59], 1.0 op_sel_hi:[1,0]
	ds_read_b128 v[64:67], v114 offset:30656
	s_waitcnt lgkmcnt(1)
	v_mfma_f32_16x16x32_bf16 v[16:19], v[8:11], v[0:3], v[76:79]
	v_sqrt_f32_e32 v56, v56
	v_sqrt_f32_e32 v57, v57
	v_rcp_f32_e32 v58, v58
	v_mfma_f32_16x16x32_bf16 v[20:23], v[8:11], v[4:7], v[72:75]
	v_rcp_f32_e32 v59, v59
	s_nop 0
	v_pk_mul_f32 v[58:59], v[96:97], v[58:59] op_sel_hi:[0,1]
	v_mfma_f32_16x16x32_bf16 v[8:11], v[12:15], v[0:3], v[84:87]
	v_exp_f32_e32 v136, v58
	v_exp_f32_e32 v137, v59
	v_mfma_f32_16x16x32_bf16 v[12:15], v[12:15], v[4:7], v[80:83]
	v_fma_f32 v58, -v136, v136, 1.0
	v_fma_f32 v59, -v137, v137, 1.0
	v_max_f32_e32 v58, 0x2b8cbccc, v58
	s_waitcnt lgkmcnt(0)
	v_mfma_f32_16x16x32_bf16 v[0:3], v[64:67], v[0:3], v[106:109]
	v_max_f32_e32 v59, 0x2b8cbccc, v59
	v_sqrt_f32_e32 v58, v58
	v_sqrt_f32_e32 v59, v59
	v_mfma_f32_16x16x32_bf16 v[4:7], v[64:67], v[4:7], v[110:113]
	v_mul_lo_u32 v64, v99, s16
	v_lshlrev_b32_e32 v65, 1, v101
	v_readlane_b32 s16, v254, 52
	s_nop 1
	v_add3_u32 v66, s16, v64, v65
	ds_read_u16 v64, v66
	ds_read_u16 v65, v66 offset:272
	s_lshl_b32 s16, s39, 12
	s_waitcnt lgkmcnt(1)
	v_lshlrev_b32_e32 v64, 16, v64
	s_waitcnt lgkmcnt(0)
	v_lshlrev_b32_e32 v65, 16, v65
	v_pk_mul_f32 v[60:61], v[60:61], v[64:65]
	s_nop 0
	v_pk_mul_f32 v[134:135], v[56:57], v[60:61]
	v_pk_add_f32 v[60:61], v[100:101], v[62:63] op_sel_hi:[0,1]
	v_exp_f32_e32 v60, v60
	v_exp_f32_e32 v61, v61
	ds_read_u16 v56, v66 offset:544
	ds_read_u16 v57, v66 offset:816
	v_fma_f32 v134, 0, v132, v134
	v_pk_add_f32 v[60:61], v[60:61], 1.0 op_sel_hi:[1,0]
	v_fmac_f32_e32 v135, v133, v134
	v_rcp_f32_e32 v60, v60
	v_rcp_f32_e32 v61, v61
	s_waitcnt lgkmcnt(1)
	v_lshlrev_b32_e32 v56, 16, v56
	s_waitcnt lgkmcnt(0)
	v_lshlrev_b32_e32 v57, 16, v57
	v_mul_f32_e32 v133, v132, v133
	v_pk_mul_f32 v[56:57], v[60:61], v[56:57]
	s_nop 0
	v_pk_mul_f32 v[130:131], v[58:59], v[56:57]
	v_lshl_add_u32 v56, v99, 14, s16
	v_ashrrev_i32_e32 v99, 5, v97
	v_add_u32_e32 v126, s26, v99
	v_ashrrev_i32_e32 v127, 31, v126
	v_lshl_add_u64 v[138:139], s[6:7], 0, v[126:127]
	v_lshlrev_b64 v[156:157], 12, v[138:139]
	ds_read_u16 v117, v66 offset:4352
	ds_read_u16 v119, v66 offset:4624
	ds_read_u16 v113, v66 offset:4896
	ds_read_u16 v115, v66 offset:5168
	ds_read_u16 v109, v66 offset:8704
	ds_read_u16 v111, v66 offset:8976
	ds_read_u16 v105, v66 offset:9248
	ds_read_u16 v107, v66 offset:9520
	ds_read_u16 v95, v66 offset:13056
	ds_read_u16 v103, v66 offset:13328
	ds_read_u16 v91, v66 offset:13600
	ds_read_u16 v93, v66 offset:13872
	ds_read_u16 v87, v66 offset:17408
	ds_read_u16 v89, v66 offset:17680
	ds_read_u16 v83, v66 offset:17952
	ds_read_u16 v85, v66 offset:18224
	ds_read_u16 v79, v66 offset:21760
	ds_read_u16 v81, v66 offset:22032
	ds_read_u16 v75, v66 offset:22304
	ds_read_u16 v77, v66 offset:22576
	ds_read_u16 v71, v66 offset:26112
	ds_read_u16 v73, v66 offset:26384
	ds_read_u16 v67, v66 offset:26656
	ds_read_u16 v69, v66 offset:26928
	ds_read_u16 v61, v66 offset:30464
	ds_read_u16 v63, v66 offset:30736
	ds_read_u16 v57, v66 offset:31008
	ds_read_u16 v59, v66 offset:31280
	v_lshl_add_u64 v[156:157], v[128:129], 0, v[156:157]
	global_load_dword v101, v[156:157], off
	v_mov_b32_e32 v186, 0x2000
	v_mov_b32_e32 v187, 0
	v_lshl_add_u64 v[188:189], v[186:187], 0, v[156:157]
	global_load_dword v200, v[188:189], off
	v_lshl_add_u64 v[190:191], v[186:187], 0, v[188:189]
	global_load_dword v201, v[190:191], off
	v_lshl_add_u64 v[188:189], v[186:187], 0, v[190:191]
	global_load_dword v202, v[188:189], off
	v_lshl_add_u64 v[190:191], v[186:187], 0, v[188:189]
	global_load_dword v203, v[190:191], off
	v_lshl_add_u64 v[188:189], v[186:187], 0, v[190:191]
	global_load_dword v204, v[188:189], off
	v_lshl_add_u64 v[190:191], v[186:187], 0, v[188:189]
	global_load_dword v205, v[190:191], off
	v_lshl_add_u64 v[188:189], v[186:187], 0, v[190:191]
	global_load_dword v206, v[188:189], off
	v_add_lshl_u32 v65, v160, v56, 1
	v_add_u32_e32 v56, 0x1800, v65
	v_add_u32_e32 v58, 0x3800, v65
	v_add_u32_e32 v60, 0x5800, v65
	v_add_u32_e32 v62, 0x7800, v65
	v_add_u32_e32 v64, 0x21800, v65
	v_add_u32_e32 v66, 0x23800, v65
	v_add_u32_e32 v68, 0x25800, v65
	v_add_u32_e32 v70, 0x27800, v65
	v_add_u32_e32 v72, 0x41800, v65
	v_add_u32_e32 v74, 0x43800, v65
	v_add_u32_e32 v76, 0x45800, v65
	v_add_u32_e32 v78, 0x47800, v65
	v_add_u32_e32 v80, 0x61800, v65
	v_add_u32_e32 v82, 0x63800, v65
	v_add_u32_e32 v84, 0x65800, v65
	v_add_u32_e32 v86, 0x67800, v65
	v_add_u32_e32 v88, 0x81800, v65
	v_add_u32_e32 v90, 0x83800, v65
	v_add_u32_e32 v92, 0x85800, v65
	v_add_u32_e32 v94, 0x87800, v65
	v_add_u32_e32 v102, 0xa1800, v65
	v_add_u32_e32 v104, 0xa3800, v65
	v_add_u32_e32 v106, 0xa5800, v65
	v_add_u32_e32 v108, 0xa7800, v65
	v_add_u32_e32 v110, 0xc1800, v65
	v_add_u32_e32 v112, 0xc3800, v65
	v_add_u32_e32 v114, 0xc5800, v65
	v_add_u32_e32 v116, 0xc7800, v65
	v_add_u32_e32 v118, 0xe1800, v65
	v_add_u32_e32 v120, 0xe3800, v65
	v_add_u32_e32 v122, 0xe5800, v65
	v_add_u32_e32 v124, 0xe7800, v65
	global_load_ushort v182, v56, s[0:1]
	global_load_ushort v183, v58, s[0:1]
	global_load_ushort v184, v60, s[0:1]
	global_load_ushort v185, v62, s[0:1]
	global_load_ushort v178, v64, s[0:1]
	global_load_ushort v179, v66, s[0:1]
	global_load_ushort v180, v68, s[0:1]
	global_load_ushort v181, v70, s[0:1]
	global_load_ushort v174, v72, s[0:1]
	global_load_ushort v175, v74, s[0:1]
	global_load_ushort v176, v76, s[0:1]
	global_load_ushort v177, v78, s[0:1]
	global_load_ushort v170, v80, s[0:1]
	global_load_ushort v171, v82, s[0:1]
	global_load_ushort v172, v84, s[0:1]
	global_load_ushort v173, v86, s[0:1]
	global_load_ushort v152, v88, s[0:1]
	global_load_ushort v153, v90, s[0:1]
	global_load_ushort v154, v92, s[0:1]
	global_load_ushort v155, v94, s[0:1]
	global_load_ushort v148, v102, s[0:1]
	global_load_ushort v149, v104, s[0:1]
	global_load_ushort v150, v106, s[0:1]
	global_load_ushort v151, v108, s[0:1]
	global_load_ushort v144, v110, s[0:1]
	global_load_ushort v145, v112, s[0:1]
	global_load_ushort v146, v114, s[0:1]
	global_load_ushort v147, v116, s[0:1]
	global_load_ushort v140, v118, s[0:1]
	global_load_ushort v141, v120, s[0:1]
	global_load_ushort v142, v122, s[0:1]
	global_load_ushort v143, v124, s[0:1]
	v_lshl_add_u32 v65, v97, 2, v231
	v_fma_f32 v130, v136, v135, v130
	v_mul_f32_e32 v136, v136, v133
	v_and_b32_e32 v65, 0xfc, v65
	v_and_b32_e32 v97, 16, v97
	v_fmac_f32_e32 v131, v137, v130
	v_mul_f32_e32 v137, v137, v136
	v_cmp_eq_u32_e64 s[36:37], 0, v97
	v_cmp_ne_u32_e64 s[34:35], 0, v97
	ds_bpermute_b32 v97, v65, v137
	ds_bpermute_b32 v99, v65, v131
	s_waitcnt vmcnt(32) lgkmcnt(0)
	v_fmac_f32_e32 v99, v101, v97
	v_cndmask_b32_e64 v156, v99, v101, s[36:37]
	v_pk_fma_f32 v[130:131], v[136:137], v[156:157], v[130:131] op_sel_hi:[1,0,1]
	v_pk_fma_f32 v[132:133], v[132:133], v[156:157], v[134:135] op_sel_hi:[1,0,1]
	s_and_saveexec_b64 s[16:17], s[34:35]
	s_cbranch_execz .LBB0_272
	v_lshlrev_b64 v[134:135], 10, v[138:139]
	v_lshl_add_u64 v[134:135], v[134:135], 2, s[8:9]
	v_lshl_add_u64 v[134:135], v[160:161], 2, v[134:135]
	v_add_co_u32_e32 v134, vcc, 0x6a60000, v134
	s_nop 1
	v_addc_co_u32_e32 v135, vcc, 0, v135, vcc
	global_store_dword v[134:135], v131, off
.LBB0_272:
	s_or_b64 exec, exec, s[16:17]
	v_mov_b32_e32 v99, v98
	v_pk_add_f32 v[48:49], v[98:99], v[48:49]
	v_mov_b32_e32 v101, v100
	v_exp_f32_e32 v48, v48
	v_exp_f32_e32 v49, v49
	v_pk_add_f32 v[52:53], v[100:101], v[52:53]
	v_pk_add_f32 v[50:51], v[98:99], v[50:51]
	v_exp_f32_e32 v52, v52
	v_pk_add_f32 v[48:49], v[48:49], 1.0 op_sel_hi:[1,0]
	v_exp_f32_e32 v53, v53
	v_rcp_f32_e32 v48, v48
	v_rcp_f32_e32 v49, v49
	v_exp_f32_e32 v50, v50
	v_exp_f32_e32 v51, v51
	v_mov_b32_e32 v97, v96
	v_pk_add_f32 v[52:53], v[52:53], 1.0 op_sel_hi:[1,0]
	v_pk_mul_f32 v[48:49], v[96:97], v[48:49]
	v_pk_add_f32 v[50:51], v[50:51], 1.0 op_sel_hi:[1,0]
	v_rcp_f32_e32 v136, v52
	v_rcp_f32_e32 v137, v53
	v_exp_f32_e32 v52, v48
	v_exp_f32_e32 v53, v49
	v_rcp_f32_e32 v50, v50
	v_rcp_f32_e32 v51, v51
	v_pk_add_f32 v[54:55], v[100:101], v[54:55]
	v_pk_fma_f32 v[48:49], v[52:53], v[52:53], 1.0 op_sel_hi:[1,1,0] neg_lo:[1,0,0] neg_hi:[1,0,0]
	v_exp_f32_e32 v54, v54
	v_exp_f32_e32 v55, v55
	v_pk_mul_f32 v[50:51], v[96:97], v[50:51]
	v_max_f32_e32 v48, 0x2b8cbccc, v48
	v_max_f32_e32 v49, 0x2b8cbccc, v49
	v_exp_f32_e32 v50, v50
	v_exp_f32_e32 v51, v51
	v_sqrt_f32_e32 v48, v48
	v_sqrt_f32_e32 v49, v49
	v_lshlrev_b32_e32 v134, 16, v117
	v_lshlrev_b32_e32 v135, 16, v119
	v_pk_add_f32 v[54:55], v[54:55], 1.0 op_sel_hi:[1,0]
	v_pk_mul_f32 v[134:135], v[136:137], v[134:135]
	v_rcp_f32_e32 v54, v54
	v_rcp_f32_e32 v55, v55
	v_pk_fma_f32 v[136:137], v[50:51], v[50:51], 1.0 op_sel_hi:[1,1,0] neg_lo:[1,0,0] neg_hi:[1,0,0]
	v_pk_mul_f32 v[134:135], v[48:49], v[134:135]
	v_lshlrev_b32_e32 v48, 16, v113
	v_max_f32_e32 v113, 0x2b8cbccc, v136
	v_sqrt_f32_e32 v136, v113
	v_max_f32_e32 v113, 0x2b8cbccc, v137
	v_lshlrev_b32_e32 v49, 16, v115
	v_sqrt_f32_e32 v137, v113
	v_pk_mul_f32 v[48:49], v[54:55], v[48:49]
	v_add_u32_e32 v54, 2, v126
	v_ashrrev_i32_e32 v55, 31, v54
	v_lshl_add_u64 v[54:55], s[6:7], 0, v[54:55]
	v_pk_mul_f32 v[48:49], v[136:137], v[48:49]
	v_lshlrev_b64 v[136:137], 12, v[54:55]
	v_lshl_add_u64 v[136:137], v[128:129], 0, v[136:137]
	v_mov_b32_e32 v117, v200
	v_fma_f32 v134, 0, v52, v134
	v_fmac_f32_e32 v135, v53, v134
	v_mul_f32_e32 v53, v52, v53
	v_fma_f32 v48, v50, v135, v48
	v_mul_f32_e32 v50, v50, v53
	v_fmac_f32_e32 v49, v51, v48
	v_mul_f32_e32 v51, v51, v50
	ds_bpermute_b32 v113, v65, v51
	ds_bpermute_b32 v115, v65, v49
	s_waitcnt vmcnt(0) lgkmcnt(0)
	v_fmac_f32_e32 v115, v117, v113
	v_cndmask_b32_e64 v136, v115, v117, s[36:37]
	v_pk_fma_f32 v[48:49], v[50:51], v[136:137], v[48:49] op_sel_hi:[1,0,1]
	v_pk_fma_f32 v[50:51], v[52:53], v[136:137], v[134:135] op_sel_hi:[1,0,1]
	s_and_saveexec_b64 s[16:17], s[34:35]
	s_cbranch_execz .LBB0_274
	v_lshlrev_b64 v[52:53], 10, v[54:55]
	v_lshl_add_u64 v[52:53], v[52:53], 2, s[8:9]
	v_lshl_add_u64 v[52:53], v[160:161], 2, v[52:53]
	v_add_co_u32_e32 v52, vcc, 0x6a60000, v52
	s_nop 1
	v_addc_co_u32_e32 v53, vcc, 0, v53, vcc
	global_store_dword v[52:53], v49, off
.LBB0_274:
	s_or_b64 exec, exec, s[16:17]
	v_pk_add_f32 v[40:41], v[98:99], v[40:41]
	v_pk_add_f32 v[42:43], v[98:99], v[42:43]
	v_exp_f32_e32 v40, v40
	v_exp_f32_e32 v41, v41
	v_pk_add_f32 v[44:45], v[100:101], v[44:45]
	v_exp_f32_e32 v42, v42
	v_exp_f32_e32 v43, v43
	v_pk_add_f32 v[40:41], v[40:41], 1.0 op_sel_hi:[1,0]
	v_exp_f32_e32 v44, v44
	v_exp_f32_e32 v45, v45
	v_rcp_f32_e32 v40, v40
	v_rcp_f32_e32 v41, v41
	v_pk_add_f32 v[42:43], v[42:43], 1.0 op_sel_hi:[1,0]
	v_pk_add_f32 v[44:45], v[44:45], 1.0 op_sel_hi:[1,0]
	v_rcp_f32_e32 v42, v42
	v_pk_mul_f32 v[40:41], v[96:97], v[40:41]
	v_rcp_f32_e32 v43, v43
	v_rcp_f32_e32 v54, v44
	v_rcp_f32_e32 v55, v45
	v_exp_f32_e32 v44, v40
	v_exp_f32_e32 v45, v41
	v_pk_add_f32 v[46:47], v[100:101], v[46:47]
	v_pk_mul_f32 v[42:43], v[96:97], v[42:43]
	v_exp_f32_e32 v46, v46
	v_exp_f32_e32 v47, v47
	v_pk_fma_f32 v[40:41], v[44:45], v[44:45], 1.0 op_sel_hi:[1,1,0] neg_lo:[1,0,0] neg_hi:[1,0,0]
	v_exp_f32_e32 v42, v42
	v_exp_f32_e32 v43, v43
	v_max_f32_e32 v40, 0x2b8cbccc, v40
	v_max_f32_e32 v41, 0x2b8cbccc, v41
	v_sqrt_f32_e32 v40, v40
	v_sqrt_f32_e32 v41, v41
	v_pk_add_f32 v[46:47], v[46:47], 1.0 op_sel_hi:[1,0]
	v_lshlrev_b32_e32 v52, 16, v109
	v_lshlrev_b32_e32 v53, 16, v111
	v_rcp_f32_e32 v46, v46
	v_rcp_f32_e32 v47, v47
	v_pk_mul_f32 v[52:53], v[54:55], v[52:53]
	v_pk_fma_f32 v[54:55], v[42:43], v[42:43], 1.0 op_sel_hi:[1,1,0] neg_lo:[1,0,0] neg_hi:[1,0,0]
	v_pk_mul_f32 v[52:53], v[40:41], v[52:53]
	v_max_f32_e32 v54, 0x2b8cbccc, v54
	v_max_f32_e32 v55, 0x2b8cbccc, v55
	v_lshlrev_b32_e32 v40, 16, v105
	v_lshlrev_b32_e32 v41, 16, v107
	v_sqrt_f32_e32 v54, v54
	v_sqrt_f32_e32 v55, v55
	v_pk_mul_f32 v[40:41], v[46:47], v[40:41]
	v_add_u32_e32 v46, 4, v126
	v_ashrrev_i32_e32 v47, 31, v46
	v_lshl_add_u64 v[46:47], s[6:7], 0, v[46:47]
	v_pk_mul_f32 v[40:41], v[54:55], v[40:41]
	v_lshlrev_b64 v[54:55], 12, v[46:47]
	v_lshl_add_u64 v[54:55], v[128:129], 0, v[54:55]
	v_mov_b32_e32 v54, v201
	v_fma_f32 v52, 0, v44, v52
	v_fmac_f32_e32 v53, v45, v52
	v_mul_f32_e32 v45, v44, v45
	v_fma_f32 v40, v42, v53, v40
	v_mul_f32_e32 v42, v42, v45
	v_fmac_f32_e32 v41, v43, v40
	v_mul_f32_e32 v43, v43, v42
	ds_bpermute_b32 v105, v65, v43
	ds_bpermute_b32 v107, v65, v41
	s_waitcnt lgkmcnt(0)
	v_fmac_f32_e32 v107, v54, v105
	v_cndmask_b32_e64 v54, v107, v54, s[36:37]
	v_pk_fma_f32 v[40:41], v[42:43], v[54:55], v[40:41] op_sel_hi:[1,0,1]
	v_pk_fma_f32 v[42:43], v[44:45], v[54:55], v[52:53] op_sel_hi:[1,0,1]
	s_and_saveexec_b64 s[16:17], s[34:35]
	s_cbranch_execz .LBB0_276
	v_lshlrev_b64 v[44:45], 10, v[46:47]
	v_lshl_add_u64 v[44:45], v[44:45], 2, s[8:9]
	v_lshl_add_u64 v[44:45], v[160:161], 2, v[44:45]
	v_add_co_u32_e32 v44, vcc, 0x6a60000, v44
	s_nop 1
	v_addc_co_u32_e32 v45, vcc, 0, v45, vcc
	global_store_dword v[44:45], v41, off
.LBB0_276:
	s_or_b64 exec, exec, s[16:17]
	v_pk_add_f32 v[32:33], v[98:99], v[32:33]
	v_pk_add_f32 v[34:35], v[98:99], v[34:35]
	v_exp_f32_e32 v32, v32
	v_exp_f32_e32 v33, v33
	v_pk_add_f32 v[36:37], v[100:101], v[36:37]
	v_exp_f32_e32 v34, v34
	v_exp_f32_e32 v35, v35
	v_pk_add_f32 v[32:33], v[32:33], 1.0 op_sel_hi:[1,0]
	v_exp_f32_e32 v36, v36
	v_exp_f32_e32 v37, v37
	v_rcp_f32_e32 v32, v32
	v_rcp_f32_e32 v33, v33
	v_pk_add_f32 v[34:35], v[34:35], 1.0 op_sel_hi:[1,0]
	v_pk_add_f32 v[36:37], v[36:37], 1.0 op_sel_hi:[1,0]
	v_rcp_f32_e32 v34, v34
	v_pk_mul_f32 v[32:33], v[96:97], v[32:33]
	v_rcp_f32_e32 v35, v35
	v_rcp_f32_e32 v46, v36
	v_rcp_f32_e32 v47, v37
	v_exp_f32_e32 v36, v32
	v_exp_f32_e32 v37, v33
	v_pk_add_f32 v[38:39], v[100:101], v[38:39]
	v_pk_mul_f32 v[34:35], v[96:97], v[34:35]
	v_exp_f32_e32 v38, v38
	v_exp_f32_e32 v39, v39
	v_pk_fma_f32 v[32:33], v[36:37], v[36:37], 1.0 op_sel_hi:[1,1,0] neg_lo:[1,0,0] neg_hi:[1,0,0]
	v_exp_f32_e32 v34, v34
	v_exp_f32_e32 v35, v35
	v_max_f32_e32 v32, 0x2b8cbccc, v32
	v_max_f32_e32 v33, 0x2b8cbccc, v33
	v_sqrt_f32_e32 v32, v32
	v_sqrt_f32_e32 v33, v33
	v_pk_add_f32 v[38:39], v[38:39], 1.0 op_sel_hi:[1,0]
	v_lshlrev_b32_e32 v44, 16, v95
	v_lshlrev_b32_e32 v45, 16, v103
	v_rcp_f32_e32 v38, v38
	v_rcp_f32_e32 v39, v39
	v_pk_mul_f32 v[44:45], v[46:47], v[44:45]
	v_pk_fma_f32 v[46:47], v[34:35], v[34:35], 1.0 op_sel_hi:[1,1,0] neg_lo:[1,0,0] neg_hi:[1,0,0]
	v_pk_mul_f32 v[44:45], v[32:33], v[44:45]
	v_max_f32_e32 v46, 0x2b8cbccc, v46
	v_max_f32_e32 v47, 0x2b8cbccc, v47
	v_lshlrev_b32_e32 v32, 16, v91
	v_lshlrev_b32_e32 v33, 16, v93
	v_sqrt_f32_e32 v46, v46
	v_sqrt_f32_e32 v47, v47
	v_pk_mul_f32 v[32:33], v[38:39], v[32:33]
	v_add_u32_e32 v38, 6, v126
	v_ashrrev_i32_e32 v39, 31, v38
	v_lshl_add_u64 v[38:39], s[6:7], 0, v[38:39]
	v_pk_mul_f32 v[32:33], v[46:47], v[32:33]
	v_lshlrev_b64 v[46:47], 12, v[38:39]
	v_lshl_add_u64 v[46:47], v[128:129], 0, v[46:47]
	v_mov_b32_e32 v46, v202
	v_fma_f32 v44, 0, v36, v44
	v_fmac_f32_e32 v45, v37, v44
	v_mul_f32_e32 v37, v36, v37
	v_fma_f32 v32, v34, v45, v32
	v_mul_f32_e32 v34, v34, v37
	v_fmac_f32_e32 v33, v35, v32
	v_mul_f32_e32 v35, v35, v34
	ds_bpermute_b32 v52, v65, v35
	ds_bpermute_b32 v53, v65, v33
	s_waitcnt lgkmcnt(0)
	v_fmac_f32_e32 v53, v46, v52
	v_cndmask_b32_e64 v46, v53, v46, s[36:37]
	v_pk_fma_f32 v[32:33], v[34:35], v[46:47], v[32:33] op_sel_hi:[1,0,1]
	v_pk_fma_f32 v[34:35], v[36:37], v[46:47], v[44:45] op_sel_hi:[1,0,1]
	s_and_saveexec_b64 s[16:17], s[34:35]
	s_cbranch_execz .LBB0_278
	v_lshlrev_b64 v[36:37], 10, v[38:39]
	v_lshl_add_u64 v[36:37], v[36:37], 2, s[8:9]
	v_lshl_add_u64 v[36:37], v[160:161], 2, v[36:37]
	v_add_co_u32_e32 v36, vcc, 0x6a60000, v36
	s_nop 1
	v_addc_co_u32_e32 v37, vcc, 0, v37, vcc
	global_store_dword v[36:37], v33, off
.LBB0_278:
	s_or_b64 exec, exec, s[16:17]
	v_pk_add_f32 v[24:25], v[98:99], v[24:25]
	v_pk_add_f32 v[26:27], v[98:99], v[26:27]
	v_exp_f32_e32 v24, v24
	v_exp_f32_e32 v25, v25
	v_pk_add_f32 v[28:29], v[100:101], v[28:29]
	v_exp_f32_e32 v26, v26
	v_exp_f32_e32 v27, v27
	v_pk_add_f32 v[24:25], v[24:25], 1.0 op_sel_hi:[1,0]
	v_exp_f32_e32 v28, v28
	v_exp_f32_e32 v29, v29
	v_rcp_f32_e32 v24, v24
	v_rcp_f32_e32 v25, v25
	v_pk_add_f32 v[26:27], v[26:27], 1.0 op_sel_hi:[1,0]
	v_pk_add_f32 v[28:29], v[28:29], 1.0 op_sel_hi:[1,0]
	v_rcp_f32_e32 v26, v26
	v_pk_mul_f32 v[24:25], v[96:97], v[24:25]
	v_rcp_f32_e32 v27, v27
	v_rcp_f32_e32 v38, v28
	v_rcp_f32_e32 v39, v29
	v_exp_f32_e32 v28, v24
	v_exp_f32_e32 v29, v25
	v_pk_add_f32 v[30:31], v[100:101], v[30:31]
	v_pk_mul_f32 v[26:27], v[96:97], v[26:27]
	v_exp_f32_e32 v30, v30
	v_exp_f32_e32 v31, v31
	v_pk_fma_f32 v[24:25], v[28:29], v[28:29], 1.0 op_sel_hi:[1,1,0] neg_lo:[1,0,0] neg_hi:[1,0,0]
	v_exp_f32_e32 v26, v26
	v_exp_f32_e32 v27, v27
	v_max_f32_e32 v24, 0x2b8cbccc, v24
	v_max_f32_e32 v25, 0x2b8cbccc, v25
	v_sqrt_f32_e32 v24, v24
	v_sqrt_f32_e32 v25, v25
	v_pk_add_f32 v[30:31], v[30:31], 1.0 op_sel_hi:[1,0]
	v_lshlrev_b32_e32 v36, 16, v87
	v_lshlrev_b32_e32 v37, 16, v89
	v_rcp_f32_e32 v30, v30
	v_rcp_f32_e32 v31, v31
	v_pk_mul_f32 v[36:37], v[38:39], v[36:37]
	v_pk_fma_f32 v[38:39], v[26:27], v[26:27], 1.0 op_sel_hi:[1,1,0] neg_lo:[1,0,0] neg_hi:[1,0,0]
	v_pk_mul_f32 v[36:37], v[24:25], v[36:37]
	v_max_f32_e32 v38, 0x2b8cbccc, v38
	v_max_f32_e32 v39, 0x2b8cbccc, v39
	v_lshlrev_b32_e32 v24, 16, v83
	v_lshlrev_b32_e32 v25, 16, v85
	v_sqrt_f32_e32 v38, v38
	v_sqrt_f32_e32 v39, v39
	v_pk_mul_f32 v[24:25], v[30:31], v[24:25]
	v_add_u32_e32 v30, 8, v126
	v_ashrrev_i32_e32 v31, 31, v30
	v_lshl_add_u64 v[30:31], s[6:7], 0, v[30:31]
	v_pk_mul_f32 v[24:25], v[38:39], v[24:25]
	v_lshlrev_b64 v[38:39], 12, v[30:31]
	v_lshl_add_u64 v[38:39], v[128:129], 0, v[38:39]
	v_mov_b32_e32 v38, v203
	v_fma_f32 v36, 0, v28, v36
	v_fmac_f32_e32 v37, v29, v36
	v_mul_f32_e32 v29, v28, v29
	v_fma_f32 v24, v26, v37, v24
	v_mul_f32_e32 v26, v26, v29
	v_fmac_f32_e32 v25, v27, v24
	v_mul_f32_e32 v27, v27, v26
	ds_bpermute_b32 v44, v65, v27
	ds_bpermute_b32 v45, v65, v25
	s_waitcnt lgkmcnt(0)
	v_fmac_f32_e32 v45, v38, v44
	v_cndmask_b32_e64 v38, v45, v38, s[36:37]
	v_pk_fma_f32 v[24:25], v[26:27], v[38:39], v[24:25] op_sel_hi:[1,0,1]
	v_pk_fma_f32 v[26:27], v[28:29], v[38:39], v[36:37] op_sel_hi:[1,0,1]
	s_and_saveexec_b64 s[16:17], s[34:35]
	s_cbranch_execz .LBB0_280
	v_lshlrev_b64 v[28:29], 10, v[30:31]
	v_lshl_add_u64 v[28:29], v[28:29], 2, s[8:9]
	v_lshl_add_u64 v[28:29], v[160:161], 2, v[28:29]
	v_add_co_u32_e32 v28, vcc, 0x6a60000, v28
	s_nop 1
	v_addc_co_u32_e32 v29, vcc, 0, v29, vcc
	global_store_dword v[28:29], v25, off
.LBB0_280:
	s_or_b64 exec, exec, s[16:17]
	v_pk_add_f32 v[16:17], v[98:99], v[16:17]
	v_pk_add_f32 v[18:19], v[98:99], v[18:19]
	v_exp_f32_e32 v16, v16
	v_exp_f32_e32 v17, v17
	v_pk_add_f32 v[20:21], v[100:101], v[20:21]
	v_exp_f32_e32 v18, v18
	v_exp_f32_e32 v19, v19
	v_pk_add_f32 v[16:17], v[16:17], 1.0 op_sel_hi:[1,0]
	v_exp_f32_e32 v20, v20
	v_exp_f32_e32 v21, v21
	v_rcp_f32_e32 v16, v16
	v_rcp_f32_e32 v17, v17
	v_pk_add_f32 v[18:19], v[18:19], 1.0 op_sel_hi:[1,0]
	v_pk_add_f32 v[20:21], v[20:21], 1.0 op_sel_hi:[1,0]
	v_rcp_f32_e32 v18, v18
	v_pk_mul_f32 v[16:17], v[96:97], v[16:17]
	v_rcp_f32_e32 v19, v19
	v_rcp_f32_e32 v30, v20
	v_rcp_f32_e32 v31, v21
	v_exp_f32_e32 v20, v16
	v_exp_f32_e32 v21, v17
	v_pk_add_f32 v[22:23], v[100:101], v[22:23]
	v_pk_mul_f32 v[18:19], v[96:97], v[18:19]
	v_exp_f32_e32 v22, v22
	v_exp_f32_e32 v23, v23
	v_pk_fma_f32 v[16:17], v[20:21], v[20:21], 1.0 op_sel_hi:[1,1,0] neg_lo:[1,0,0] neg_hi:[1,0,0]
	v_exp_f32_e32 v18, v18
	v_exp_f32_e32 v19, v19
	v_max_f32_e32 v16, 0x2b8cbccc, v16
	v_max_f32_e32 v17, 0x2b8cbccc, v17
	v_sqrt_f32_e32 v16, v16
	v_sqrt_f32_e32 v17, v17
	v_pk_add_f32 v[22:23], v[22:23], 1.0 op_sel_hi:[1,0]
	v_lshlrev_b32_e32 v28, 16, v79
	v_lshlrev_b32_e32 v29, 16, v81
	v_rcp_f32_e32 v22, v22
	v_rcp_f32_e32 v23, v23
	v_pk_mul_f32 v[28:29], v[30:31], v[28:29]
	v_pk_fma_f32 v[30:31], v[18:19], v[18:19], 1.0 op_sel_hi:[1,1,0] neg_lo:[1,0,0] neg_hi:[1,0,0]
	v_pk_mul_f32 v[28:29], v[16:17], v[28:29]
	v_max_f32_e32 v30, 0x2b8cbccc, v30
	v_max_f32_e32 v31, 0x2b8cbccc, v31
	v_lshlrev_b32_e32 v16, 16, v75
	v_lshlrev_b32_e32 v17, 16, v77
	v_sqrt_f32_e32 v30, v30
	v_sqrt_f32_e32 v31, v31
	v_pk_mul_f32 v[16:17], v[22:23], v[16:17]
	v_add_u32_e32 v22, 10, v126
	v_ashrrev_i32_e32 v23, 31, v22
	v_lshl_add_u64 v[22:23], s[6:7], 0, v[22:23]
	v_pk_mul_f32 v[16:17], v[30:31], v[16:17]
	v_lshlrev_b64 v[30:31], 12, v[22:23]
	v_lshl_add_u64 v[30:31], v[128:129], 0, v[30:31]
	v_mov_b32_e32 v30, v204
	v_fma_f32 v28, 0, v20, v28
	v_fmac_f32_e32 v29, v21, v28
	v_mul_f32_e32 v21, v20, v21
	v_fma_f32 v16, v18, v29, v16
	v_mul_f32_e32 v18, v18, v21
	v_fmac_f32_e32 v17, v19, v16
	v_mul_f32_e32 v19, v19, v18
	ds_bpermute_b32 v36, v65, v19
	ds_bpermute_b32 v37, v65, v17
	s_waitcnt lgkmcnt(0)
	v_fmac_f32_e32 v37, v30, v36
	v_cndmask_b32_e64 v30, v37, v30, s[36:37]
	v_pk_fma_f32 v[16:17], v[18:19], v[30:31], v[16:17] op_sel_hi:[1,0,1]
	v_pk_fma_f32 v[18:19], v[20:21], v[30:31], v[28:29] op_sel_hi:[1,0,1]
	s_and_saveexec_b64 s[16:17], s[34:35]
	s_cbranch_execz .LBB0_282
	v_lshlrev_b64 v[20:21], 10, v[22:23]
	v_lshl_add_u64 v[20:21], v[20:21], 2, s[8:9]
	v_lshl_add_u64 v[20:21], v[160:161], 2, v[20:21]
	v_add_co_u32_e32 v20, vcc, 0x6a60000, v20
	s_nop 1
	v_addc_co_u32_e32 v21, vcc, 0, v21, vcc
	global_store_dword v[20:21], v17, off
.LBB0_282:
	s_or_b64 exec, exec, s[16:17]
	v_pk_add_f32 v[8:9], v[98:99], v[8:9]
	v_pk_add_f32 v[10:11], v[98:99], v[10:11]
	v_exp_f32_e32 v8, v8
	v_exp_f32_e32 v9, v9
	v_pk_add_f32 v[12:13], v[100:101], v[12:13]
	v_exp_f32_e32 v10, v10
	v_exp_f32_e32 v11, v11
	v_pk_add_f32 v[8:9], v[8:9], 1.0 op_sel_hi:[1,0]
	v_exp_f32_e32 v12, v12
	v_exp_f32_e32 v13, v13
	v_rcp_f32_e32 v8, v8
	v_rcp_f32_e32 v9, v9
	v_pk_add_f32 v[10:11], v[10:11], 1.0 op_sel_hi:[1,0]
	v_pk_add_f32 v[12:13], v[12:13], 1.0 op_sel_hi:[1,0]
	v_rcp_f32_e32 v10, v10
	v_pk_mul_f32 v[8:9], v[96:97], v[8:9]
	v_rcp_f32_e32 v11, v11
	v_rcp_f32_e32 v22, v12
	v_rcp_f32_e32 v23, v13
	v_exp_f32_e32 v12, v8
	v_exp_f32_e32 v13, v9
	v_pk_add_f32 v[14:15], v[100:101], v[14:15]
	v_pk_mul_f32 v[10:11], v[96:97], v[10:11]
	v_exp_f32_e32 v14, v14
	v_exp_f32_e32 v15, v15
	v_pk_fma_f32 v[8:9], v[12:13], v[12:13], 1.0 op_sel_hi:[1,1,0] neg_lo:[1,0,0] neg_hi:[1,0,0]
	v_exp_f32_e32 v10, v10
	v_exp_f32_e32 v11, v11
	v_max_f32_e32 v8, 0x2b8cbccc, v8
	v_max_f32_e32 v9, 0x2b8cbccc, v9
	v_sqrt_f32_e32 v8, v8
	v_sqrt_f32_e32 v9, v9
	v_pk_add_f32 v[14:15], v[14:15], 1.0 op_sel_hi:[1,0]
	v_lshlrev_b32_e32 v20, 16, v71
	v_lshlrev_b32_e32 v21, 16, v73
	v_rcp_f32_e32 v14, v14
	v_rcp_f32_e32 v15, v15
	v_pk_mul_f32 v[20:21], v[22:23], v[20:21]
	v_pk_fma_f32 v[22:23], v[10:11], v[10:11], 1.0 op_sel_hi:[1,1,0] neg_lo:[1,0,0] neg_hi:[1,0,0]
	v_pk_mul_f32 v[20:21], v[8:9], v[20:21]
	v_max_f32_e32 v22, 0x2b8cbccc, v22
	v_max_f32_e32 v23, 0x2b8cbccc, v23
	v_lshlrev_b32_e32 v8, 16, v67
	v_lshlrev_b32_e32 v9, 16, v69
	v_sqrt_f32_e32 v22, v22
	v_sqrt_f32_e32 v23, v23
	v_pk_mul_f32 v[8:9], v[14:15], v[8:9]
	v_add_u32_e32 v14, 12, v126
	v_ashrrev_i32_e32 v15, 31, v14
	v_lshl_add_u64 v[14:15], s[6:7], 0, v[14:15]
	v_pk_mul_f32 v[8:9], v[22:23], v[8:9]
	v_lshlrev_b64 v[22:23], 12, v[14:15]
	v_lshl_add_u64 v[22:23], v[128:129], 0, v[22:23]
	v_mov_b32_e32 v22, v205
	v_fma_f32 v20, 0, v12, v20
	v_fmac_f32_e32 v21, v13, v20
	v_mul_f32_e32 v13, v12, v13
	v_fma_f32 v8, v10, v21, v8
	v_mul_f32_e32 v10, v10, v13
	v_fmac_f32_e32 v9, v11, v8
	v_mul_f32_e32 v11, v11, v10
	ds_bpermute_b32 v28, v65, v11
	ds_bpermute_b32 v29, v65, v9
	s_waitcnt lgkmcnt(0)
	v_fmac_f32_e32 v29, v22, v28
	v_cndmask_b32_e64 v22, v29, v22, s[36:37]
	v_pk_fma_f32 v[8:9], v[10:11], v[22:23], v[8:9] op_sel_hi:[1,0,1]
	v_pk_fma_f32 v[10:11], v[12:13], v[22:23], v[20:21] op_sel_hi:[1,0,1]
	s_and_saveexec_b64 s[16:17], s[34:35]
	s_cbranch_execz .LBB0_284
	v_lshlrev_b64 v[12:13], 10, v[14:15]
	v_lshl_add_u64 v[12:13], v[12:13], 2, s[8:9]
	v_lshl_add_u64 v[12:13], v[160:161], 2, v[12:13]
	v_add_co_u32_e32 v12, vcc, 0x6a60000, v12
	s_nop 1
	v_addc_co_u32_e32 v13, vcc, 0, v13, vcc
	global_store_dword v[12:13], v9, off
.LBB0_284:
	s_or_b64 exec, exec, s[16:17]
	v_add_u32_e32 v12, 14, v126
	v_ashrrev_i32_e32 v13, 31, v12
	v_lshl_add_u64 v[12:13], s[6:7], 0, v[12:13]
	v_lshlrev_b64 v[14:15], 12, v[12:13]
	v_lshl_add_u64 v[14:15], v[128:129], 0, v[14:15]
	v_mov_b32_e32 v30, v206
	v_pk_add_f32 v[0:1], v[98:99], v[0:1]
	v_pk_add_f32 v[2:3], v[98:99], v[2:3]
	v_exp_f32_e32 v0, v0
	v_exp_f32_e32 v1, v1
	v_exp_f32_e32 v2, v2
	v_exp_f32_e32 v3, v3
	v_pk_add_f32 v[6:7], v[100:101], v[6:7]
	v_pk_add_f32 v[0:1], v[0:1], 1.0 op_sel_hi:[1,0]
	v_pk_add_f32 v[4:5], v[100:101], v[4:5]
	v_rcp_f32_e32 v0, v0
	v_rcp_f32_e32 v1, v1
	v_pk_add_f32 v[2:3], v[2:3], 1.0 op_sel_hi:[1,0]
	v_exp_f32_e32 v6, v6
	v_rcp_f32_e32 v2, v2
	v_rcp_f32_e32 v3, v3
	v_exp_f32_e32 v7, v7
	v_pk_mul_f32 v[0:1], v[96:97], v[0:1]
	v_exp_f32_e32 v4, v4
	v_exp_f32_e32 v5, v5
	v_exp_f32_e32 v22, v0
	v_exp_f32_e32 v23, v1
	v_pk_mul_f32 v[2:3], v[96:97], v[2:3]
	v_pk_add_f32 v[6:7], v[6:7], 1.0 op_sel_hi:[1,0]
	v_exp_f32_e32 v0, v2
	v_exp_f32_e32 v1, v3
	v_pk_add_f32 v[4:5], v[4:5], 1.0 op_sel_hi:[1,0]
	v_rcp_f32_e32 v2, v6
	v_rcp_f32_e32 v3, v7
	v_pk_fma_f32 v[6:7], v[22:23], v[22:23], 1.0 op_sel_hi:[1,1,0] neg_lo:[1,0,0] neg_hi:[1,0,0]
	v_rcp_f32_e32 v4, v4
	v_rcp_f32_e32 v5, v5
	v_max_f32_e32 v6, 0x2b8cbccc, v6
	v_max_f32_e32 v7, 0x2b8cbccc, v7
	v_pk_fma_f32 v[28:29], v[0:1], v[0:1], 1.0 op_sel_hi:[1,1,0] neg_lo:[1,0,0] neg_hi:[1,0,0]
	v_sqrt_f32_e32 v6, v6
	v_sqrt_f32_e32 v7, v7
	v_max_f32_e32 v28, 0x2b8cbccc, v28
	v_max_f32_e32 v29, 0x2b8cbccc, v29
	v_lshlrev_b32_e32 v14, 16, v61
	v_lshlrev_b32_e32 v15, 16, v63
	v_sqrt_f32_e32 v28, v28
	v_sqrt_f32_e32 v29, v29
	v_pk_mul_f32 v[4:5], v[4:5], v[14:15]
	v_lshlrev_b32_e32 v20, 16, v57
	v_lshlrev_b32_e32 v21, 16, v59
	v_pk_mul_f32 v[4:5], v[6:7], v[4:5]
	v_pk_mul_f32 v[2:3], v[2:3], v[20:21]
	v_fma_f32 v4, 0, v22, v4
	v_pk_mul_f32 v[2:3], v[28:29], v[2:3]
	v_fmac_f32_e32 v5, v23, v4
	v_mul_f32_e32 v23, v22, v23
	v_fma_f32 v2, v0, v5, v2
	v_mul_f32_e32 v0, v0, v23
	v_fmac_f32_e32 v3, v1, v2
	v_mul_f32_e32 v1, v1, v0
	ds_bpermute_b32 v6, v65, v1
	ds_bpermute_b32 v7, v65, v3
	s_waitcnt lgkmcnt(0)
	v_fmac_f32_e32 v7, v30, v6
	v_cndmask_b32_e64 v6, v7, v30, s[36:37]
	v_pk_fma_f32 v[0:1], v[0:1], v[6:7], v[2:3] op_sel_hi:[1,0,1]
	v_pk_fma_f32 v[2:3], v[22:23], v[6:7], v[4:5] op_sel_hi:[1,0,1]
	s_and_saveexec_b64 s[16:17], s[34:35]
	s_cbranch_execz .LBB0_286
	v_lshlrev_b64 v[4:5], 10, v[12:13]
	v_lshl_add_u64 v[4:5], v[4:5], 2, s[8:9]
	v_lshl_add_u64 v[4:5], v[160:161], 2, v[4:5]
	v_add_co_u32_e32 v4, vcc, 0x6a60000, v4
	s_nop 1
	v_addc_co_u32_e32 v5, vcc, 0, v5, vcc
	global_store_dword v[4:5], v1, off

.LBB0_287:
	s_and_b64 vcc, exec, s[16:17]
	s_cbranch_vccz .LBB0_300
	s_or_b32 s16, s38, s61
	s_lshl_b32 s16, s16, 8
	v_readlane_b32 s17, v254, 51
	v_mbcnt_lo_u32_b32 v2, -1, 0
	v_mbcnt_hi_u32_b32 v2, -1, v2
	s_add_i32 s16, s16, s17
	v_and_or_b32 v160, v2, 15, s16
	v_readlane_b32 s16, v253, 50
	v_ashrrev_i32_e32 v2, 1, v2
	v_lshlrev_b64 v[0:1], 9, v[160:161]
	v_readlane_b32 s17, v253, 51
	v_and_b32_e32 v2, -8, v2
	v_ashrrev_i32_e32 v3, 31, v2
	v_lshl_add_u64 v[0:1], s[16:17], 0, v[0:1]
	v_lshl_add_u64 v[0:1], v[2:3], 1, v[0:1]
	s_movk_i32 s16, 0x2000
	v_add_co_u32_e32 v4, vcc, s16, v0
	s_cmp_lt_i32 s38, 2
	s_nop 0
	v_addc_co_u32_e32 v5, vcc, 0, v1, vcc
	global_load_dwordx4 v[56:59], v[0:1], off
	global_load_dwordx4 v[48:51], v[0:1], off offset:64
	global_load_dwordx4 v[60:63], v[4:5], off
	global_load_dwordx4 v[52:55], v[4:5], off offset:64
	global_load_dwordx4 v[40:43], v[0:1], off offset:128
	global_load_dwordx4 v[32:35], v[0:1], off offset:192
	global_load_dwordx4 v[44:47], v[4:5], off offset:128
	global_load_dwordx4 v[36:39], v[4:5], off offset:192
	global_load_dwordx4 v[24:27], v[0:1], off offset:256
	global_load_dwordx4 v[16:19], v[0:1], off offset:320
	global_load_dwordx4 v[28:31], v[4:5], off offset:256
	global_load_dwordx4 v[20:23], v[4:5], off offset:320
	global_load_dwordx4 v[8:11], v[0:1], off offset:384
	s_nop 0
	global_load_dwordx4 v[0:3], v[0:1], off offset:448
	s_nop 0
	global_load_dwordx4 v[12:15], v[4:5], off offset:384
	s_nop 0
	global_load_dwordx4 v[4:7], v[4:5], off offset:448
	v_mbcnt_lo_u32_b32 v64, -1, 0
	v_mbcnt_hi_u32_b32 v64, -1, v64
	s_mov_b64 s[16:17], -1
	v_add_u32_e32 v65, s3, v64
	v_lshlrev_b32_e32 v64, 3, v64
	v_ashrrev_i32_e32 v170, 5, v65
	v_and_b32_e32 v171, 0xf8, v64
	s_cbranch_scc1 .LBB0_294
	s_cmp_gt_i32 s38, 2
	s_cbranch_scc0 .LBB0_291
	s_lshr_b32 s16, s40, 3
	v_add_u32_e32 v226, s16, v170
	v_readlane_b32 s48, v252, 4
	v_readlane_b32 s49, v252, 5
	v_lshlrev_b32_e32 v160, 1, v171
	v_lshlrev_b32_e32 v227, 3, v226
	v_add_u32_e32 v226, s6, v226
	v_mul_u32_u24_e32 v226, 0xf000, v226
	v_lshl_add_u32 v226, v171, 2, v226
	v_add_u32_e32 v229, 0x8000000, v160
	v_lshl_add_u32 v227, v227, 13, v229
	global_load_dwordx4 v[64:67], v226, s[48:49] offset:3072
	global_load_dwordx4 v[68:71], v226, s[48:49] offset:3088
	v_add_u32_e32 v213, 0x1000, v226
	global_load_dwordx4 v[72:75], v213, s[48:49] offset:3072
	global_load_dwordx4 v[76:79], v213, s[48:49] offset:3088
	v_add_u32_e32 v214, 0x2000, v226
	global_load_dwordx4 v[80:83], v214, s[48:49] offset:3072
	global_load_dwordx4 v[84:87], v214, s[48:49] offset:3088
	v_add_u32_e32 v215, 0x3000, v226
	global_load_dwordx4 v[88:91], v215, s[48:49] offset:3072
	global_load_dwordx4 v[92:95], v215, s[48:49] offset:3088
	v_add_u32_e32 v212, 0x4000, v226
	global_load_dwordx4 v[96:99], v212, s[48:49] offset:3072
	global_load_dwordx4 v[100:103], v212, s[48:49] offset:3088
	v_add_u32_e32 v213, 0x5000, v226
	global_load_dwordx4 v[104:107], v213, s[48:49] offset:3072
	global_load_dwordx4 v[108:111], v213, s[48:49] offset:3088
	v_add_u32_e32 v214, 0x6000, v226
	global_load_dwordx4 v[112:115], v214, s[48:49] offset:3072
	global_load_dwordx4 v[116:119], v214, s[48:49] offset:3088
	v_add_u32_e32 v215, 0x7000, v226
	global_load_dwordx4 v[120:123], v215, s[48:49] offset:3072
	global_load_dwordx4 v[124:127], v215, s[48:49] offset:3088
	v_add_u32_e32 v212, 0x8000, v226
	global_load_dwordx4 v[128:131], v212, s[48:49] offset:3072
	global_load_dwordx4 v[132:135], v212, s[48:49] offset:3088
	v_add_u32_e32 v213, 0x9000, v226
	global_load_dwordx4 v[136:139], v213, s[48:49] offset:3072
	global_load_dwordx4 v[140:143], v213, s[48:49] offset:3088
	v_add_u32_e32 v214, 0xa000, v226
	global_load_dwordx4 v[144:147], v214, s[48:49] offset:3072
	global_load_dwordx4 v[148:151], v214, s[48:49] offset:3088
	v_add_u32_e32 v215, 0xb000, v226
	global_load_dwordx4 v[172:175], v215, s[48:49] offset:3072
	global_load_dwordx4 v[176:179], v215, s[48:49] offset:3088
	v_add_u32_e32 v212, 0xc000, v226
	global_load_dwordx4 v[180:183], v212, s[48:49] offset:3072
	global_load_dwordx4 v[184:187], v212, s[48:49] offset:3088
	v_add_u32_e32 v213, 0xd000, v226
	global_load_dwordx4 v[188:191], v213, s[48:49] offset:3072
	global_load_dwordx4 v[192:195], v213, s[48:49] offset:3088
	v_add_u32_e32 v214, 0xe000, v226
	global_load_dwordx4 v[196:199], v214, s[48:49] offset:3072
	global_load_dwordx4 v[200:203], v214, s[48:49] offset:3088
	global_load_dwordx4 v[232:235], v227, s[0:1] offset:1536
	v_add_u32_e32 v213, 0x2000, v227
	global_load_dwordx4 v[236:239], v213, s[0:1] offset:1536
	v_add_u32_e32 v214, 0x4000, v227
	global_load_dwordx4 v[240:243], v214, s[0:1] offset:1536
	v_add_u32_e32 v215, 0x6000, v227
	global_load_dwordx4 v[244:247], v215, s[0:1] offset:1536
	v_add_u32_e32 v212, 0x8000, v227
	global_load_dwordx4 v[248:251], v212, s[0:1] offset:1536
	s_mov_b32 s44, 0xffff0000
	s_mov_b32 s45, 0x3d800000
	v_mul_u32_u24_e32 v229, 0x1080, v170
	v_add_u32_e32 v160, v229, v160
	v_mov_b64_e32 v[204:205], 0
	v_mov_b64_e32 v[206:207], 0
	v_mov_b64_e32 v[208:209], 0
	v_mov_b64_e32 v[210:211], 0
	s_waitcnt vmcnt(33)
	v_cvt_pk_bf16_f32 v64, v64, v65
	v_cvt_pk_bf16_f32 v65, v66, v67
	v_cvt_pk_bf16_f32 v66, v68, v69
	v_cvt_pk_bf16_f32 v67, v70, v71
	v_add_u32_e32 v213, 0xa000, v227
	global_load_dwordx4 v[68:71], v213, s[0:1] offset:1536
	v_lshlrev_b32_e32 v212, 16, v64
	v_and_b32_e32 v213, s44, v64
	v_lshlrev_b32_e32 v214, 16, v65
	v_and_b32_e32 v215, s44, v65
	v_lshlrev_b32_e32 v216, 16, v66
	v_and_b32_e32 v217, s44, v66
	v_lshlrev_b32_e32 v222, 16, v67
	v_and_b32_e32 v223, s44, v67
	v_pk_add_f32 v[204:205], v[204:205], v[212:213]
	v_pk_add_f32 v[206:207], v[206:207], v[214:215]
	v_pk_add_f32 v[208:209], v[208:209], v[216:217]
	v_pk_add_f32 v[210:211], v[210:211], v[222:223]
	s_waitcnt vmcnt(32)
	v_cvt_pk_bf16_f32 v72, v72, v73
	v_cvt_pk_bf16_f32 v73, v74, v75
	v_cvt_pk_bf16_f32 v74, v76, v77
	v_cvt_pk_bf16_f32 v75, v78, v79
	v_add_u32_e32 v214, 0xc000, v227
	global_load_dwordx4 v[76:79], v214, s[0:1] offset:1536
	v_lshlrev_b32_e32 v212, 16, v72
	v_and_b32_e32 v213, s44, v72
	v_lshlrev_b32_e32 v214, 16, v73
	v_and_b32_e32 v215, s44, v73
	v_lshlrev_b32_e32 v216, 16, v74
	v_and_b32_e32 v217, s44, v74
	v_lshlrev_b32_e32 v222, 16, v75
	v_and_b32_e32 v223, s44, v75
	v_pk_add_f32 v[204:205], v[204:205], v[212:213]
	v_pk_add_f32 v[206:207], v[206:207], v[214:215]
	v_pk_add_f32 v[208:209], v[208:209], v[216:217]
	v_pk_add_f32 v[210:211], v[210:211], v[222:223]
	s_waitcnt vmcnt(31)
	v_cvt_pk_bf16_f32 v80, v80, v81
	v_cvt_pk_bf16_f32 v81, v82, v83
	v_cvt_pk_bf16_f32 v82, v84, v85
	v_cvt_pk_bf16_f32 v83, v86, v87
	v_add_u32_e32 v215, 0xe000, v227
	global_load_dwordx4 v[84:87], v215, s[0:1] offset:1536
	v_lshlrev_b32_e32 v212, 16, v80
	v_and_b32_e32 v213, s44, v80
	v_lshlrev_b32_e32 v214, 16, v81
	v_and_b32_e32 v215, s44, v81
	v_lshlrev_b32_e32 v216, 16, v82
	v_and_b32_e32 v217, s44, v82
	v_lshlrev_b32_e32 v222, 16, v83
	v_and_b32_e32 v223, s44, v83
	v_pk_add_f32 v[204:205], v[204:205], v[212:213]
	v_pk_add_f32 v[206:207], v[206:207], v[214:215]
	v_pk_add_f32 v[208:209], v[208:209], v[216:217]
	v_pk_add_f32 v[210:211], v[210:211], v[222:223]
	s_waitcnt vmcnt(30)
	v_cvt_pk_bf16_f32 v88, v88, v89
	v_cvt_pk_bf16_f32 v89, v90, v91
	v_cvt_pk_bf16_f32 v90, v92, v93
	v_cvt_pk_bf16_f32 v91, v94, v95
	v_lshlrev_b32_e32 v212, 16, v88
	v_and_b32_e32 v213, s44, v88
	v_lshlrev_b32_e32 v214, 16, v89
	v_and_b32_e32 v215, s44, v89
	v_lshlrev_b32_e32 v216, 16, v90
	v_and_b32_e32 v217, s44, v90
	v_lshlrev_b32_e32 v222, 16, v91
	v_and_b32_e32 v223, s44, v91
	v_pk_add_f32 v[204:205], v[204:205], v[212:213]
	v_pk_add_f32 v[206:207], v[206:207], v[214:215]
	v_pk_add_f32 v[208:209], v[208:209], v[216:217]
	v_pk_add_f32 v[210:211], v[210:211], v[222:223]
	s_waitcnt vmcnt(28)
	v_cvt_pk_bf16_f32 v96, v96, v97
	v_cvt_pk_bf16_f32 v97, v98, v99
	v_cvt_pk_bf16_f32 v98, v100, v101
	v_cvt_pk_bf16_f32 v99, v102, v103
	v_lshlrev_b32_e32 v212, 16, v96
	v_and_b32_e32 v213, s44, v96
	v_lshlrev_b32_e32 v214, 16, v97
	v_and_b32_e32 v215, s44, v97
	v_lshlrev_b32_e32 v216, 16, v98
	v_and_b32_e32 v217, s44, v98
	v_lshlrev_b32_e32 v222, 16, v99
	v_and_b32_e32 v223, s44, v99
	v_pk_add_f32 v[204:205], v[204:205], v[212:213]
	v_pk_add_f32 v[206:207], v[206:207], v[214:215]
	v_pk_add_f32 v[208:209], v[208:209], v[216:217]
	v_pk_add_f32 v[210:211], v[210:211], v[222:223]
	s_waitcnt vmcnt(26)
	v_cvt_pk_bf16_f32 v104, v104, v105
	v_cvt_pk_bf16_f32 v105, v106, v107
	v_cvt_pk_bf16_f32 v106, v108, v109
	v_cvt_pk_bf16_f32 v107, v110, v111
	v_lshlrev_b32_e32 v212, 16, v104
	v_and_b32_e32 v213, s44, v104
	v_lshlrev_b32_e32 v214, 16, v105
	v_and_b32_e32 v215, s44, v105
	v_lshlrev_b32_e32 v216, 16, v106
	v_and_b32_e32 v217, s44, v106
	v_lshlrev_b32_e32 v222, 16, v107
	v_and_b32_e32 v223, s44, v107
	v_pk_add_f32 v[204:205], v[204:205], v[212:213]
	v_pk_add_f32 v[206:207], v[206:207], v[214:215]
	v_pk_add_f32 v[208:209], v[208:209], v[216:217]
	v_pk_add_f32 v[210:211], v[210:211], v[222:223]
	s_waitcnt vmcnt(24)
	v_cvt_pk_bf16_f32 v112, v112, v113
	v_cvt_pk_bf16_f32 v113, v114, v115
	v_cvt_pk_bf16_f32 v114, v116, v117
	v_cvt_pk_bf16_f32 v115, v118, v119
	v_lshlrev_b32_e32 v212, 16, v112
	v_and_b32_e32 v213, s44, v112
	v_lshlrev_b32_e32 v214, 16, v113
	v_and_b32_e32 v215, s44, v113
	v_lshlrev_b32_e32 v216, 16, v114
	v_and_b32_e32 v217, s44, v114
	v_lshlrev_b32_e32 v222, 16, v115
	v_and_b32_e32 v223, s44, v115
	v_pk_add_f32 v[204:205], v[204:205], v[212:213]
	v_pk_add_f32 v[206:207], v[206:207], v[214:215]
	v_pk_add_f32 v[208:209], v[208:209], v[216:217]
	v_pk_add_f32 v[210:211], v[210:211], v[222:223]
	s_waitcnt vmcnt(22)
	v_cvt_pk_bf16_f32 v120, v120, v121
	v_cvt_pk_bf16_f32 v121, v122, v123
	v_cvt_pk_bf16_f32 v122, v124, v125
	v_cvt_pk_bf16_f32 v123, v126, v127
	v_lshlrev_b32_e32 v212, 16, v120
	v_and_b32_e32 v213, s44, v120
	v_lshlrev_b32_e32 v214, 16, v121
	v_and_b32_e32 v215, s44, v121
	v_lshlrev_b32_e32 v216, 16, v122
	v_and_b32_e32 v217, s44, v122
	v_lshlrev_b32_e32 v222, 16, v123
	v_and_b32_e32 v223, s44, v123
	v_pk_add_f32 v[204:205], v[204:205], v[212:213]
	v_pk_add_f32 v[206:207], v[206:207], v[214:215]
	v_pk_add_f32 v[208:209], v[208:209], v[216:217]
	v_pk_add_f32 v[210:211], v[210:211], v[222:223]
	s_waitcnt vmcnt(20)
	v_cvt_pk_bf16_f32 v128, v128, v129
	v_cvt_pk_bf16_f32 v129, v130, v131
	v_cvt_pk_bf16_f32 v130, v132, v133
	v_cvt_pk_bf16_f32 v131, v134, v135
	v_lshlrev_b32_e32 v212, 16, v128
	v_and_b32_e32 v213, s44, v128
	v_lshlrev_b32_e32 v214, 16, v129
	v_and_b32_e32 v215, s44, v129
	v_lshlrev_b32_e32 v216, 16, v130
	v_and_b32_e32 v217, s44, v130
	v_lshlrev_b32_e32 v222, 16, v131
	v_and_b32_e32 v223, s44, v131
	v_pk_add_f32 v[204:205], v[204:205], v[212:213]
	v_pk_add_f32 v[206:207], v[206:207], v[214:215]
	v_pk_add_f32 v[208:209], v[208:209], v[216:217]
	v_pk_add_f32 v[210:211], v[210:211], v[222:223]
	s_waitcnt vmcnt(18)
	v_cvt_pk_bf16_f32 v136, v136, v137
	v_cvt_pk_bf16_f32 v137, v138, v139
	v_cvt_pk_bf16_f32 v138, v140, v141
	v_cvt_pk_bf16_f32 v139, v142, v143
	v_lshlrev_b32_e32 v212, 16, v136
	v_and_b32_e32 v213, s44, v136
	v_lshlrev_b32_e32 v214, 16, v137
	v_and_b32_e32 v215, s44, v137
	v_lshlrev_b32_e32 v216, 16, v138
	v_and_b32_e32 v217, s44, v138
	v_lshlrev_b32_e32 v222, 16, v139
	v_and_b32_e32 v223, s44, v139
	v_pk_add_f32 v[204:205], v[204:205], v[212:213]
	v_pk_add_f32 v[206:207], v[206:207], v[214:215]
	v_pk_add_f32 v[208:209], v[208:209], v[216:217]
	v_pk_add_f32 v[210:211], v[210:211], v[222:223]
	s_waitcnt vmcnt(16)
	v_cvt_pk_bf16_f32 v144, v144, v145
	v_cvt_pk_bf16_f32 v145, v146, v147
	v_cvt_pk_bf16_f32 v146, v148, v149
	v_cvt_pk_bf16_f32 v147, v150, v151
	v_lshlrev_b32_e32 v212, 16, v144
	v_and_b32_e32 v213, s44, v144
	v_lshlrev_b32_e32 v214, 16, v145
	v_and_b32_e32 v215, s44, v145
	v_lshlrev_b32_e32 v216, 16, v146
	v_and_b32_e32 v217, s44, v146
	v_lshlrev_b32_e32 v222, 16, v147
	v_and_b32_e32 v223, s44, v147
	v_pk_add_f32 v[204:205], v[204:205], v[212:213]
	v_pk_add_f32 v[206:207], v[206:207], v[214:215]
	v_pk_add_f32 v[208:209], v[208:209], v[216:217]
	v_pk_add_f32 v[210:211], v[210:211], v[222:223]
	s_waitcnt vmcnt(14)
	v_cvt_pk_bf16_f32 v172, v172, v173
	v_cvt_pk_bf16_f32 v173, v174, v175
	v_cvt_pk_bf16_f32 v174, v176, v177
	v_cvt_pk_bf16_f32 v175, v178, v179
	v_lshlrev_b32_e32 v212, 16, v172
	v_and_b32_e32 v213, s44, v172
	v_lshlrev_b32_e32 v214, 16, v173
	v_and_b32_e32 v215, s44, v173
	v_lshlrev_b32_e32 v216, 16, v174
	v_and_b32_e32 v217, s44, v174
	v_lshlrev_b32_e32 v222, 16, v175
	v_and_b32_e32 v223, s44, v175
	v_pk_add_f32 v[204:205], v[204:205], v[212:213]
	v_pk_add_f32 v[206:207], v[206:207], v[214:215]
	v_pk_add_f32 v[208:209], v[208:209], v[216:217]
	v_pk_add_f32 v[210:211], v[210:211], v[222:223]
	s_waitcnt vmcnt(12)
	v_cvt_pk_bf16_f32 v180, v180, v181
	v_cvt_pk_bf16_f32 v181, v182, v183
	v_cvt_pk_bf16_f32 v182, v184, v185
	v_cvt_pk_bf16_f32 v183, v186, v187
	v_lshlrev_b32_e32 v212, 16, v180
	v_and_b32_e32 v213, s44, v180
	v_lshlrev_b32_e32 v214, 16, v181
	v_and_b32_e32 v215, s44, v181
	v_lshlrev_b32_e32 v216, 16, v182
	v_and_b32_e32 v217, s44, v182
	v_lshlrev_b32_e32 v222, 16, v183
	v_and_b32_e32 v223, s44, v183
	v_pk_add_f32 v[204:205], v[204:205], v[212:213]
	v_pk_add_f32 v[206:207], v[206:207], v[214:215]
	v_pk_add_f32 v[208:209], v[208:209], v[216:217]
	v_pk_add_f32 v[210:211], v[210:211], v[222:223]
	s_waitcnt vmcnt(10)
	v_cvt_pk_bf16_f32 v188, v188, v189
	v_cvt_pk_bf16_f32 v189, v190, v191
	v_cvt_pk_bf16_f32 v190, v192, v193
	v_cvt_pk_bf16_f32 v191, v194, v195
	v_lshlrev_b32_e32 v212, 16, v188
	v_and_b32_e32 v213, s44, v188
	v_lshlrev_b32_e32 v214, 16, v189
	v_and_b32_e32 v215, s44, v189
	v_lshlrev_b32_e32 v216, 16, v190
	v_and_b32_e32 v217, s44, v190
	v_lshlrev_b32_e32 v222, 16, v191
	v_and_b32_e32 v223, s44, v191
	v_pk_add_f32 v[204:205], v[204:205], v[212:213]
	v_pk_add_f32 v[206:207], v[206:207], v[214:215]
	v_pk_add_f32 v[208:209], v[208:209], v[216:217]
	v_pk_add_f32 v[210:211], v[210:211], v[222:223]
	s_waitcnt vmcnt(8)
	v_cvt_pk_bf16_f32 v196, v196, v197
	v_cvt_pk_bf16_f32 v197, v198, v199
	v_cvt_pk_bf16_f32 v198, v200, v201
	v_cvt_pk_bf16_f32 v199, v202, v203
	v_lshlrev_b32_e32 v212, 16, v196
	v_and_b32_e32 v213, s44, v196
	v_lshlrev_b32_e32 v214, 16, v197
	v_and_b32_e32 v215, s44, v197
	v_lshlrev_b32_e32 v216, 16, v198
	v_and_b32_e32 v217, s44, v198
	v_lshlrev_b32_e32 v222, 16, v199
	v_and_b32_e32 v223, s44, v199
	v_pk_add_f32 v[204:205], v[204:205], v[212:213]
	v_pk_add_f32 v[206:207], v[206:207], v[214:215]
	v_pk_add_f32 v[208:209], v[208:209], v[216:217]
	v_pk_add_f32 v[210:211], v[210:211], v[222:223]
	s_waitcnt vmcnt(7)
	v_lshlrev_b32_e32 v212, 16, v232
	v_and_b32_e32 v213, s44, v232
	v_lshlrev_b32_e32 v214, 16, v233
	v_and_b32_e32 v215, s44, v233
	v_lshlrev_b32_e32 v216, 16, v234
	v_and_b32_e32 v217, s44, v234
	v_lshlrev_b32_e32 v222, 16, v235
	v_and_b32_e32 v223, s44, v235
	v_pk_add_f32 v[204:205], v[204:205], v[212:213]
	v_pk_add_f32 v[206:207], v[206:207], v[214:215]
	v_pk_add_f32 v[208:209], v[208:209], v[216:217]
	v_pk_add_f32 v[210:211], v[210:211], v[222:223]
	v_fma_f32 v224, v204, s45, -v212
	v_fma_f32 v225, v205, s45, -v213
	v_cvt_pk_bf16_f32 v152, v224, v225
	v_fma_f32 v224, v206, s45, -v214
	v_fma_f32 v225, v207, s45, -v215
	v_cvt_pk_bf16_f32 v153, v224, v225
	v_fma_f32 v224, v208, s45, -v216
	v_fma_f32 v225, v209, s45, -v217
	v_cvt_pk_bf16_f32 v154, v224, v225
	v_fma_f32 v224, v210, s45, -v222
	v_fma_f32 v225, v211, s45, -v223
	v_cvt_pk_bf16_f32 v155, v224, v225
	ds_write_b128 v160, v[152:155]
	v_lshlrev_b32_e32 v212, 16, v64
	v_and_b32_e32 v213, s44, v64
	v_lshlrev_b32_e32 v214, 16, v65
	v_and_b32_e32 v215, s44, v65
	v_lshlrev_b32_e32 v216, 16, v66
	v_and_b32_e32 v217, s44, v66
	v_lshlrev_b32_e32 v222, 16, v67
	v_and_b32_e32 v223, s44, v67
	v_pk_add_f32 v[204:205], v[204:205], v[212:213] neg_lo:[0,1] neg_hi:[0,1]
	v_pk_add_f32 v[206:207], v[206:207], v[214:215] neg_lo:[0,1] neg_hi:[0,1]
	v_pk_add_f32 v[208:209], v[208:209], v[216:217] neg_lo:[0,1] neg_hi:[0,1]
	v_pk_add_f32 v[210:211], v[210:211], v[222:223] neg_lo:[0,1] neg_hi:[0,1]
	s_waitcnt vmcnt(6)
	v_lshlrev_b32_e32 v212, 16, v236
	v_and_b32_e32 v213, s44, v236
	v_lshlrev_b32_e32 v214, 16, v237
	v_and_b32_e32 v215, s44, v237
	v_lshlrev_b32_e32 v216, 16, v238
	v_and_b32_e32 v217, s44, v238
	v_lshlrev_b32_e32 v222, 16, v239
	v_and_b32_e32 v223, s44, v239
	v_pk_add_f32 v[204:205], v[204:205], v[212:213]
	v_pk_add_f32 v[206:207], v[206:207], v[214:215]
	v_pk_add_f32 v[208:209], v[208:209], v[216:217]
	v_pk_add_f32 v[210:211], v[210:211], v[222:223]
	v_fma_f32 v224, v204, s45, -v212
	v_fma_f32 v225, v205, s45, -v213
	v_cvt_pk_bf16_f32 v152, v224, v225
	v_fma_f32 v224, v206, s45, -v214
	v_fma_f32 v225, v207, s45, -v215
	v_cvt_pk_bf16_f32 v153, v224, v225
	v_fma_f32 v224, v208, s45, -v216
	v_fma_f32 v225, v209, s45, -v217
	v_cvt_pk_bf16_f32 v154, v224, v225
	v_fma_f32 v224, v210, s45, -v222
	v_fma_f32 v225, v211, s45, -v223
	v_cvt_pk_bf16_f32 v155, v224, v225
	ds_write_b128 v160, v[152:155] offset:528
	v_lshlrev_b32_e32 v212, 16, v72
	v_and_b32_e32 v213, s44, v72
	v_lshlrev_b32_e32 v214, 16, v73
	v_and_b32_e32 v215, s44, v73
	v_lshlrev_b32_e32 v216, 16, v74
	v_and_b32_e32 v217, s44, v74
	v_lshlrev_b32_e32 v222, 16, v75
	v_and_b32_e32 v223, s44, v75
	v_pk_add_f32 v[204:205], v[204:205], v[212:213] neg_lo:[0,1] neg_hi:[0,1]
	v_pk_add_f32 v[206:207], v[206:207], v[214:215] neg_lo:[0,1] neg_hi:[0,1]
	v_pk_add_f32 v[208:209], v[208:209], v[216:217] neg_lo:[0,1] neg_hi:[0,1]
	v_pk_add_f32 v[210:211], v[210:211], v[222:223] neg_lo:[0,1] neg_hi:[0,1]
	s_waitcnt vmcnt(5)
	v_lshlrev_b32_e32 v212, 16, v240
	v_and_b32_e32 v213, s44, v240
	v_lshlrev_b32_e32 v214, 16, v241
	v_and_b32_e32 v215, s44, v241
	v_lshlrev_b32_e32 v216, 16, v242
	v_and_b32_e32 v217, s44, v242
	v_lshlrev_b32_e32 v222, 16, v243
	v_and_b32_e32 v223, s44, v243
	v_pk_add_f32 v[204:205], v[204:205], v[212:213]
	v_pk_add_f32 v[206:207], v[206:207], v[214:215]
	v_pk_add_f32 v[208:209], v[208:209], v[216:217]
	v_pk_add_f32 v[210:211], v[210:211], v[222:223]
	v_fma_f32 v224, v204, s45, -v212
	v_fma_f32 v225, v205, s45, -v213
	v_cvt_pk_bf16_f32 v152, v224, v225
	v_fma_f32 v224, v206, s45, -v214
	v_fma_f32 v225, v207, s45, -v215
	v_cvt_pk_bf16_f32 v153, v224, v225
	v_fma_f32 v224, v208, s45, -v216
	v_fma_f32 v225, v209, s45, -v217
	v_cvt_pk_bf16_f32 v154, v224, v225
	v_fma_f32 v224, v210, s45, -v222
	v_fma_f32 v225, v211, s45, -v223
	v_cvt_pk_bf16_f32 v155, v224, v225
	ds_write_b128 v160, v[152:155] offset:1056
	v_lshlrev_b32_e32 v212, 16, v80
	v_and_b32_e32 v213, s44, v80
	v_lshlrev_b32_e32 v214, 16, v81
	v_and_b32_e32 v215, s44, v81
	v_lshlrev_b32_e32 v216, 16, v82
	v_and_b32_e32 v217, s44, v82
	v_lshlrev_b32_e32 v222, 16, v83
	v_and_b32_e32 v223, s44, v83
	v_pk_add_f32 v[204:205], v[204:205], v[212:213] neg_lo:[0,1] neg_hi:[0,1]
	v_pk_add_f32 v[206:207], v[206:207], v[214:215] neg_lo:[0,1] neg_hi:[0,1]
	v_pk_add_f32 v[208:209], v[208:209], v[216:217] neg_lo:[0,1] neg_hi:[0,1]
	v_pk_add_f32 v[210:211], v[210:211], v[222:223] neg_lo:[0,1] neg_hi:[0,1]
	s_waitcnt vmcnt(4)
	v_lshlrev_b32_e32 v212, 16, v244
	v_and_b32_e32 v213, s44, v244
	v_lshlrev_b32_e32 v214, 16, v245
	v_and_b32_e32 v215, s44, v245
	v_lshlrev_b32_e32 v216, 16, v246
	v_and_b32_e32 v217, s44, v246
	v_lshlrev_b32_e32 v222, 16, v247
	v_and_b32_e32 v223, s44, v247
	v_pk_add_f32 v[204:205], v[204:205], v[212:213]
	v_pk_add_f32 v[206:207], v[206:207], v[214:215]
	v_pk_add_f32 v[208:209], v[208:209], v[216:217]
	v_pk_add_f32 v[210:211], v[210:211], v[222:223]
	v_fma_f32 v224, v204, s45, -v212
	v_fma_f32 v225, v205, s45, -v213
	v_cvt_pk_bf16_f32 v152, v224, v225
	v_fma_f32 v224, v206, s45, -v214
	v_fma_f32 v225, v207, s45, -v215
	v_cvt_pk_bf16_f32 v153, v224, v225
	v_fma_f32 v224, v208, s45, -v216
	v_fma_f32 v225, v209, s45, -v217
	v_cvt_pk_bf16_f32 v154, v224, v225
	v_fma_f32 v224, v210, s45, -v222
	v_fma_f32 v225, v211, s45, -v223
	v_cvt_pk_bf16_f32 v155, v224, v225
	ds_write_b128 v160, v[152:155] offset:1584
	v_lshlrev_b32_e32 v212, 16, v88
	v_and_b32_e32 v213, s44, v88
	v_lshlrev_b32_e32 v214, 16, v89
	v_and_b32_e32 v215, s44, v89
	v_lshlrev_b32_e32 v216, 16, v90
	v_and_b32_e32 v217, s44, v90
	v_lshlrev_b32_e32 v222, 16, v91
	v_and_b32_e32 v223, s44, v91
	v_pk_add_f32 v[204:205], v[204:205], v[212:213] neg_lo:[0,1] neg_hi:[0,1]
	v_pk_add_f32 v[206:207], v[206:207], v[214:215] neg_lo:[0,1] neg_hi:[0,1]
	v_pk_add_f32 v[208:209], v[208:209], v[216:217] neg_lo:[0,1] neg_hi:[0,1]
	v_pk_add_f32 v[210:211], v[210:211], v[222:223] neg_lo:[0,1] neg_hi:[0,1]
	s_waitcnt vmcnt(3)
	v_lshlrev_b32_e32 v212, 16, v248
	v_and_b32_e32 v213, s44, v248
	v_lshlrev_b32_e32 v214, 16, v249
	v_and_b32_e32 v215, s44, v249
	v_lshlrev_b32_e32 v216, 16, v250
	v_and_b32_e32 v217, s44, v250
	v_lshlrev_b32_e32 v222, 16, v251
	v_and_b32_e32 v223, s44, v251
	v_pk_add_f32 v[204:205], v[204:205], v[212:213]
	v_pk_add_f32 v[206:207], v[206:207], v[214:215]
	v_pk_add_f32 v[208:209], v[208:209], v[216:217]
	v_pk_add_f32 v[210:211], v[210:211], v[222:223]
	v_fma_f32 v224, v204, s45, -v212
	v_fma_f32 v225, v205, s45, -v213
	v_cvt_pk_bf16_f32 v152, v224, v225
	v_fma_f32 v224, v206, s45, -v214
	v_fma_f32 v225, v207, s45, -v215
	v_cvt_pk_bf16_f32 v153, v224, v225
	v_fma_f32 v224, v208, s45, -v216
	v_fma_f32 v225, v209, s45, -v217
	v_cvt_pk_bf16_f32 v154, v224, v225
	v_fma_f32 v224, v210, s45, -v222
	v_fma_f32 v225, v211, s45, -v223
	v_cvt_pk_bf16_f32 v155, v224, v225
	ds_write_b128 v160, v[152:155] offset:2112
	v_lshlrev_b32_e32 v212, 16, v96
	v_and_b32_e32 v213, s44, v96
	v_lshlrev_b32_e32 v214, 16, v97
	v_and_b32_e32 v215, s44, v97
	v_lshlrev_b32_e32 v216, 16, v98
	v_and_b32_e32 v217, s44, v98
	v_lshlrev_b32_e32 v222, 16, v99
	v_and_b32_e32 v223, s44, v99
	v_pk_add_f32 v[204:205], v[204:205], v[212:213] neg_lo:[0,1] neg_hi:[0,1]
	v_pk_add_f32 v[206:207], v[206:207], v[214:215] neg_lo:[0,1] neg_hi:[0,1]
	v_pk_add_f32 v[208:209], v[208:209], v[216:217] neg_lo:[0,1] neg_hi:[0,1]
	v_pk_add_f32 v[210:211], v[210:211], v[222:223] neg_lo:[0,1] neg_hi:[0,1]
	s_waitcnt vmcnt(2)
	v_lshlrev_b32_e32 v212, 16, v68
	v_and_b32_e32 v213, s44, v68
	v_lshlrev_b32_e32 v214, 16, v69
	v_and_b32_e32 v215, s44, v69
	v_lshlrev_b32_e32 v216, 16, v70
	v_and_b32_e32 v217, s44, v70
	v_lshlrev_b32_e32 v222, 16, v71
	v_and_b32_e32 v223, s44, v71
	v_pk_add_f32 v[204:205], v[204:205], v[212:213]
	v_pk_add_f32 v[206:207], v[206:207], v[214:215]
	v_pk_add_f32 v[208:209], v[208:209], v[216:217]
	v_pk_add_f32 v[210:211], v[210:211], v[222:223]
	v_fma_f32 v224, v204, s45, -v212
	v_fma_f32 v225, v205, s45, -v213
	v_cvt_pk_bf16_f32 v152, v224, v225
	v_fma_f32 v224, v206, s45, -v214
	v_fma_f32 v225, v207, s45, -v215
	v_cvt_pk_bf16_f32 v153, v224, v225
	v_fma_f32 v224, v208, s45, -v216
	v_fma_f32 v225, v209, s45, -v217
	v_cvt_pk_bf16_f32 v154, v224, v225
	v_fma_f32 v224, v210, s45, -v222
	v_fma_f32 v225, v211, s45, -v223
	v_cvt_pk_bf16_f32 v155, v224, v225
	ds_write_b128 v160, v[152:155] offset:2640
	v_lshlrev_b32_e32 v212, 16, v104
	v_and_b32_e32 v213, s44, v104
	v_lshlrev_b32_e32 v214, 16, v105
	v_and_b32_e32 v215, s44, v105
	v_lshlrev_b32_e32 v216, 16, v106
	v_and_b32_e32 v217, s44, v106
	v_lshlrev_b32_e32 v222, 16, v107
	v_and_b32_e32 v223, s44, v107
	v_pk_add_f32 v[204:205], v[204:205], v[212:213] neg_lo:[0,1] neg_hi:[0,1]
	v_pk_add_f32 v[206:207], v[206:207], v[214:215] neg_lo:[0,1] neg_hi:[0,1]
	v_pk_add_f32 v[208:209], v[208:209], v[216:217] neg_lo:[0,1] neg_hi:[0,1]
	v_pk_add_f32 v[210:211], v[210:211], v[222:223] neg_lo:[0,1] neg_hi:[0,1]
	s_waitcnt vmcnt(1)
	v_lshlrev_b32_e32 v212, 16, v76
	v_and_b32_e32 v213, s44, v76
	v_lshlrev_b32_e32 v214, 16, v77
	v_and_b32_e32 v215, s44, v77
	v_lshlrev_b32_e32 v216, 16, v78
	v_and_b32_e32 v217, s44, v78
	v_lshlrev_b32_e32 v222, 16, v79
	v_and_b32_e32 v223, s44, v79
	v_pk_add_f32 v[204:205], v[204:205], v[212:213]
	v_pk_add_f32 v[206:207], v[206:207], v[214:215]
	v_pk_add_f32 v[208:209], v[208:209], v[216:217]
	v_pk_add_f32 v[210:211], v[210:211], v[222:223]
	v_fma_f32 v224, v204, s45, -v212
	v_fma_f32 v225, v205, s45, -v213
	v_cvt_pk_bf16_f32 v152, v224, v225
	v_fma_f32 v224, v206, s45, -v214
	v_fma_f32 v225, v207, s45, -v215
	v_cvt_pk_bf16_f32 v153, v224, v225
	v_fma_f32 v224, v208, s45, -v216
	v_fma_f32 v225, v209, s45, -v217
	v_cvt_pk_bf16_f32 v154, v224, v225
	v_fma_f32 v224, v210, s45, -v222
	v_fma_f32 v225, v211, s45, -v223
	v_cvt_pk_bf16_f32 v155, v224, v225
	ds_write_b128 v160, v[152:155] offset:3168
	v_lshlrev_b32_e32 v212, 16, v112
	v_and_b32_e32 v213, s44, v112
	v_lshlrev_b32_e32 v214, 16, v113
	v_and_b32_e32 v215, s44, v113
	v_lshlrev_b32_e32 v216, 16, v114
	v_and_b32_e32 v217, s44, v114
	v_lshlrev_b32_e32 v222, 16, v115
	v_and_b32_e32 v223, s44, v115
	v_pk_add_f32 v[204:205], v[204:205], v[212:213] neg_lo:[0,1] neg_hi:[0,1]
	v_pk_add_f32 v[206:207], v[206:207], v[214:215] neg_lo:[0,1] neg_hi:[0,1]
	v_pk_add_f32 v[208:209], v[208:209], v[216:217] neg_lo:[0,1] neg_hi:[0,1]
	v_pk_add_f32 v[210:211], v[210:211], v[222:223] neg_lo:[0,1] neg_hi:[0,1]
	s_waitcnt vmcnt(0)
	v_lshlrev_b32_e32 v212, 16, v84
	v_and_b32_e32 v213, s44, v84
	v_lshlrev_b32_e32 v214, 16, v85
	v_and_b32_e32 v215, s44, v85
	v_lshlrev_b32_e32 v216, 16, v86
	v_and_b32_e32 v217, s44, v86
	v_lshlrev_b32_e32 v222, 16, v87
	v_and_b32_e32 v223, s44, v87
	v_pk_add_f32 v[204:205], v[204:205], v[212:213]
	v_pk_add_f32 v[206:207], v[206:207], v[214:215]
	v_pk_add_f32 v[208:209], v[208:209], v[216:217]
	v_pk_add_f32 v[210:211], v[210:211], v[222:223]
	v_fma_f32 v224, v204, s45, -v212
	v_fma_f32 v225, v205, s45, -v213
	v_cvt_pk_bf16_f32 v64, v224, v225
	v_fma_f32 v224, v206, s45, -v214
	v_fma_f32 v225, v207, s45, -v215
	v_cvt_pk_bf16_f32 v65, v224, v225
	v_fma_f32 v224, v208, s45, -v216
	v_fma_f32 v225, v209, s45, -v217
	v_cvt_pk_bf16_f32 v66, v224, v225
	v_fma_f32 v224, v210, s45, -v222
	v_fma_f32 v225, v211, s45, -v223
	v_cvt_pk_bf16_f32 v67, v224, v225
	v_mov_b32_e32 v96, v160
	s_mov_b64 s[16:17], 0

.LBB0_308:
	global_load_dwordx2 v[220:221], v[148:149], off sc1
	global_load_dwordx2 v[218:219], v[150:151], off sc1
	global_load_dwordx2 v[216:217], v[152:153], off sc1
	global_load_dwordx2 v[214:215], v[154:155], off sc1
	global_load_dwordx2 v[212:213], v[170:171], off sc1
	global_load_dwordx2 v[208:209], v[174:175], off sc1
	global_load_dwordx2 v[204:205], v[178:179], off sc1
	global_load_dwordx2 v[200:201], v[182:183], off sc1
	global_load_dwordx2 v[196:197], v[186:187], off sc1
	global_load_dwordx2 v[192:193], v[190:191], off sc1
	global_load_dwordx2 v[188:189], v[194:195], off sc1
	global_load_dwordx2 v[184:185], v[198:199], off sc1
	global_load_dwordx2 v[180:181], v[202:203], off sc1
	global_load_dwordx2 v[176:177], v[206:207], off sc1
	global_load_dwordx2 v[172:173], v[210:211], off sc1
	s_waitcnt vmcnt(0)
	v_cmp_ge_u64_e64 s[16:17], s[14:15], v[220:221]
	v_cmp_ge_u64_e32 vcc, s[14:15], v[218:219]
	s_and_b64 vcc, vcc, s[36:37]
	s_or_b64 s[16:17], s[16:17], vcc
	v_cmp_ge_u64_e32 vcc, s[14:15], v[216:217]
	s_and_b64 vcc, vcc, s[38:39]
	s_or_b64 s[16:17], s[16:17], vcc
	v_cmp_ge_u64_e32 vcc, s[14:15], v[214:215]
	s_and_b64 vcc, vcc, s[40:41]
	s_or_b64 s[16:17], s[16:17], vcc
	v_cmp_ge_u64_e32 vcc, s[14:15], v[212:213]
	s_and_b64 vcc, vcc, s[42:43]
	s_or_b64 s[16:17], s[16:17], vcc
	v_cmp_ge_u64_e32 vcc, s[14:15], v[208:209]
	s_and_b64 vcc, vcc, s[44:45]
	s_or_b64 s[16:17], s[16:17], vcc
	v_cmp_ge_u64_e32 vcc, s[14:15], v[204:205]
	s_and_b64 vcc, vcc, s[46:47]
	s_or_b64 s[16:17], s[16:17], vcc
	v_cmp_ge_u64_e32 vcc, s[14:15], v[200:201]
	s_and_b64 vcc, vcc, s[48:49]
	s_or_b64 s[16:17], s[16:17], vcc
	v_cmp_ge_u64_e32 vcc, s[14:15], v[196:197]
	s_and_b64 vcc, vcc, s[50:51]
	s_or_b64 s[16:17], s[16:17], vcc
	v_cmp_ge_u64_e32 vcc, s[14:15], v[192:193]
	s_and_b64 vcc, vcc, s[52:53]
	s_or_b64 s[16:17], s[16:17], vcc
	v_cmp_ge_u64_e32 vcc, s[14:15], v[188:189]
	s_and_b64 vcc, vcc, s[54:55]
	s_or_b64 s[16:17], s[16:17], vcc
	v_cmp_ge_u64_e32 vcc, s[14:15], v[184:185]
	s_and_b64 vcc, vcc, s[56:57]
	s_or_b64 s[16:17], s[16:17], vcc
	v_cmp_ge_u64_e32 vcc, s[14:15], v[180:181]
	s_and_b64 vcc, vcc, s[58:59]
	s_or_b64 s[16:17], s[16:17], vcc
	v_cmp_ge_u64_e32 vcc, s[14:15], v[176:177]
	s_and_b64 vcc, vcc, s[60:61]
	s_or_b64 s[16:17], s[16:17], vcc
	v_cmp_ge_u64_e32 vcc, s[14:15], v[172:173]
	s_and_b64 vcc, vcc, s[62:63]
	s_or_b64 s[16:17], s[16:17], vcc
	s_and_b64 s[16:17], s[16:17], exec
	s_cmp_eq_u64 s[16:17], 0
	s_cbranch_scc1 .LBB0_338
	s_add_i32 s28, s28, -1
	s_cmp_eq_u32 s28, 0
	s_cbranch_scc1 .LBB0_338
	s_sleep 2
	s_branch .LBB0_308

.LBB0_342:
	s_and_b64 vcc, exec, s[16:17]
	s_cbranch_vccz .LBB0_356
	s_add_i32 s16, s61, s25
	s_ashr_i32 s17, s16, 31
	s_lshl_b64 s[16:17], s[16:17], 8
	v_readlane_b32 s27, v254, 51
	s_add_u32 s16, s16, s27
	v_mbcnt_lo_u32_b32 v2, -1, 0
	v_mbcnt_hi_u32_b32 v2, -1, v2
	s_addc_u32 s17, s17, 0
	v_and_or_b32 v0, v2, 15, s16
	v_mov_b32_e32 v1, s17
	v_readlane_b32 s16, v253, 50
	v_ashrrev_i32_e32 v2, 1, v2
	v_lshlrev_b64 v[0:1], 9, v[0:1]
	v_readlane_b32 s17, v253, 51
	v_and_b32_e32 v2, -8, v2
	v_ashrrev_i32_e32 v3, 31, v2
	v_lshl_add_u64 v[0:1], s[16:17], 0, v[0:1]
	v_lshl_add_u64 v[0:1], v[2:3], 1, v[0:1]
	s_movk_i32 s16, 0x2000
	v_add_co_u32_e32 v4, vcc, s16, v0
	s_ashr_i32 s16, s68, 31
	s_nop 0
	v_addc_co_u32_e32 v5, vcc, 0, v1, vcc
	global_load_dwordx4 v[56:59], v[0:1], off
	global_load_dwordx4 v[48:51], v[0:1], off offset:64
	global_load_dwordx4 v[60:63], v[4:5], off
	global_load_dwordx4 v[52:55], v[4:5], off offset:64
	global_load_dwordx4 v[40:43], v[0:1], off offset:128
	global_load_dwordx4 v[32:35], v[0:1], off offset:192
	global_load_dwordx4 v[44:47], v[4:5], off offset:128
	global_load_dwordx4 v[36:39], v[4:5], off offset:192
	global_load_dwordx4 v[24:27], v[0:1], off offset:256
	global_load_dwordx4 v[16:19], v[0:1], off offset:320
	global_load_dwordx4 v[28:31], v[4:5], off offset:256
	global_load_dwordx4 v[20:23], v[4:5], off offset:320
	global_load_dwordx4 v[8:11], v[0:1], off offset:384
	s_nop 0
	global_load_dwordx4 v[0:3], v[0:1], off offset:448
	s_nop 0
	global_load_dwordx4 v[12:15], v[4:5], off offset:384
	s_nop 0
	global_load_dwordx4 v[4:7], v[4:5], off offset:448
	s_lshr_b32 s16, s16, 21
	v_mbcnt_lo_u32_b32 v64, -1, 0
	v_mbcnt_hi_u32_b32 v64, -1, v64
	s_add_i32 s16, s68, s16
	v_add_u32_e32 v65, s3, v64
	v_ashrrev_i32_e32 v178, 2, v65
	s_and_b32 s17, s16, 0xfffff800
	v_and_b32_e32 v180, -8, v178
	s_sub_i32 s17, s68, s17
	s_ashr_i32 s16, s16, 11
	v_add_u32_e32 v179, s17, v180
	s_ashr_i32 s17, s16, 31
	v_lshlrev_b32_e32 v64, 3, v64
	s_lshl_b64 s[42:43], s[16:17], 24
	s_and_b32 s26, s26, 0xff
	v_and_b32_e32 v181, 0xf8, v64
	s_cmp_lt_i32 s26, 1
	s_mov_b64 s[16:17], -1
	s_cbranch_scc1 .LBB0_353
	s_and_b32 s26, 0xffff, s26
	s_cmp_lt_i32 s26, 2
	s_cbranch_scc1 .LBB0_350
	v_max_i32_e32 v64, 7, v179
	v_max_i32_e32 v65, 6, v179
	v_max_i32_e32 v66, 5, v179
	v_max_i32_e32 v67, 4, v179
	s_cmp_lg_u32 s26, 2
	v_cmp_lt_i32_e64 s[38:39], 6, v179
	v_cmp_lt_i32_e64 s[36:37], 5, v179
	v_cmp_lt_i32_e64 s[34:35], 4, v179
	v_cmp_lt_i32_e32 vcc, 3, v179
	v_add_u32_e32 v176, -7, v64
	v_add_u32_e32 v174, -6, v65
	v_add_u32_e32 v172, -5, v66
	v_add_u32_e32 v170, -4, v67
	s_cbranch_scc0 .LBB0_347
	s_add_u32 s16, s10, s42
	s_addc_u32 s17, s11, s43
	s_add_u32 s16, s16, 0x5a00600
	s_addc_u32 s17, s17, 0
	v_lshlrev_b32_e32 v160, 1, v181
	v_add_u32_e32 v162, -15, v179
	v_max_i32_e32 v182, 0, v162
	v_lshl_add_u32 v182, v182, 13, v160
	global_load_dwordx4 v[64:67], v182, s[16:17]
	v_add_u32_e32 v183, 1, v162
	v_max_i32_e32 v183, 0, v183
	v_lshl_add_u32 v183, v183, 13, v160
	global_load_dwordx4 v[68:71], v183, s[16:17]
	v_add_u32_e32 v184, 2, v162
	v_max_i32_e32 v184, 0, v184
	v_lshl_add_u32 v184, v184, 13, v160
	global_load_dwordx4 v[72:75], v184, s[16:17]
	v_add_u32_e32 v185, 3, v162
	v_max_i32_e32 v185, 0, v185
	v_lshl_add_u32 v185, v185, 13, v160
	global_load_dwordx4 v[76:79], v185, s[16:17]
	v_add_u32_e32 v186, 4, v162
	v_max_i32_e32 v186, 0, v186
	v_lshl_add_u32 v186, v186, 13, v160
	global_load_dwordx4 v[80:83], v186, s[16:17]
	v_add_u32_e32 v187, 5, v162
	v_max_i32_e32 v187, 0, v187
	v_lshl_add_u32 v187, v187, 13, v160
	global_load_dwordx4 v[84:87], v187, s[16:17]
	v_add_u32_e32 v188, 6, v162
	v_max_i32_e32 v188, 0, v188
	v_lshl_add_u32 v188, v188, 13, v160
	global_load_dwordx4 v[88:91], v188, s[16:17]
	v_add_u32_e32 v189, 7, v162
	v_max_i32_e32 v189, 0, v189
	v_lshl_add_u32 v189, v189, 13, v160
	global_load_dwordx4 v[92:95], v189, s[16:17]
	v_add_u32_e32 v190, 8, v162
	v_max_i32_e32 v190, 0, v190
	v_lshl_add_u32 v190, v190, 13, v160
	global_load_dwordx4 v[96:99], v190, s[16:17]
	v_add_u32_e32 v191, 9, v162
	v_max_i32_e32 v191, 0, v191
	v_lshl_add_u32 v191, v191, 13, v160
	global_load_dwordx4 v[100:103], v191, s[16:17]
	v_add_u32_e32 v192, 10, v162
	v_max_i32_e32 v192, 0, v192
	v_lshl_add_u32 v192, v192, 13, v160
	global_load_dwordx4 v[104:107], v192, s[16:17]
	v_add_u32_e32 v193, 11, v162
	v_max_i32_e32 v193, 0, v193
	v_lshl_add_u32 v193, v193, 13, v160
	global_load_dwordx4 v[108:111], v193, s[16:17]
	v_add_u32_e32 v194, 12, v162
	v_max_i32_e32 v194, 0, v194
	v_lshl_add_u32 v194, v194, 13, v160
	global_load_dwordx4 v[112:115], v194, s[16:17]
	v_add_u32_e32 v195, 13, v162
	v_max_i32_e32 v195, 0, v195
	v_lshl_add_u32 v195, v195, 13, v160
	global_load_dwordx4 v[116:119], v195, s[16:17]
	v_add_u32_e32 v196, 14, v162
	v_max_i32_e32 v196, 0, v196
	v_lshl_add_u32 v196, v196, 13, v160
	global_load_dwordx4 v[120:123], v196, s[16:17]
	v_lshl_add_u32 v197, v179, 13, v160
	global_load_dwordx4 v[124:127], v197, s[16:17]
	v_add_u32_e32 v198, 1, v179
	v_lshl_add_u32 v198, v198, 13, v160
	global_load_dwordx4 v[128:131], v198, s[16:17]
	v_add_u32_e32 v199, 2, v179
	v_lshl_add_u32 v199, v199, 13, v160
	global_load_dwordx4 v[132:135], v199, s[16:17]
	v_add_u32_e32 v200, 3, v179
	v_lshl_add_u32 v200, v200, 13, v160
	global_load_dwordx4 v[136:139], v200, s[16:17]
	v_add_u32_e32 v201, 4, v179
	v_lshl_add_u32 v201, v201, 13, v160
	global_load_dwordx4 v[140:143], v201, s[16:17]
	v_add_u32_e32 v202, 5, v179
	v_lshl_add_u32 v202, v202, 13, v160
	global_load_dwordx4 v[144:147], v202, s[16:17]
	v_add_u32_e32 v203, 6, v179
	v_lshl_add_u32 v203, v203, 13, v160
	global_load_dwordx4 v[148:151], v203, s[16:17]
	v_add_u32_e32 v204, 7, v179
	v_lshl_add_u32 v204, v204, 13, v160
	global_load_dwordx4 v[152:155], v204, s[16:17]
	s_mov_b32 s41, 0xffff0000
	v_mul_u32_u24_e32 v208, 0x210, v180
	s_and_b32 s40, s68, 0x780
	v_add_u32_e32 v208, v208, v160
	s_cbranch_scc1 .Lw16p_nz
	s_waitcnt vmcnt(0)
	v_cmp_lt_i32_e32 vcc, 14, v179
	s_nop 1
	v_cndmask_b32_e32 v64, 0, v64, vcc
	v_cndmask_b32_e32 v65, 0, v65, vcc
	v_cndmask_b32_e32 v66, 0, v66, vcc
	v_cndmask_b32_e32 v67, 0, v67, vcc
	v_cmp_lt_i32_e32 vcc, 13, v179
	s_nop 1
	v_cndmask_b32_e32 v68, 0, v68, vcc
	v_cndmask_b32_e32 v69, 0, v69, vcc
	v_cndmask_b32_e32 v70, 0, v70, vcc
	v_cndmask_b32_e32 v71, 0, v71, vcc
	v_cmp_lt_i32_e32 vcc, 12, v179
	s_nop 1
	v_cndmask_b32_e32 v72, 0, v72, vcc
	v_cndmask_b32_e32 v73, 0, v73, vcc
	v_cndmask_b32_e32 v74, 0, v74, vcc
	v_cndmask_b32_e32 v75, 0, v75, vcc
	v_cmp_lt_i32_e32 vcc, 11, v179
	s_nop 1
	v_cndmask_b32_e32 v76, 0, v76, vcc
	v_cndmask_b32_e32 v77, 0, v77, vcc
	v_cndmask_b32_e32 v78, 0, v78, vcc
	v_cndmask_b32_e32 v79, 0, v79, vcc
	v_cmp_lt_i32_e32 vcc, 10, v179
	s_nop 1
	v_cndmask_b32_e32 v80, 0, v80, vcc
	v_cndmask_b32_e32 v81, 0, v81, vcc
	v_cndmask_b32_e32 v82, 0, v82, vcc
	v_cndmask_b32_e32 v83, 0, v83, vcc
	v_cmp_lt_i32_e32 vcc, 9, v179
	s_nop 1
	v_cndmask_b32_e32 v84, 0, v84, vcc
	v_cndmask_b32_e32 v85, 0, v85, vcc
	v_cndmask_b32_e32 v86, 0, v86, vcc
	v_cndmask_b32_e32 v87, 0, v87, vcc
	v_cmp_lt_i32_e32 vcc, 8, v179
	s_nop 1
	v_cndmask_b32_e32 v88, 0, v88, vcc
	v_cndmask_b32_e32 v89, 0, v89, vcc
	v_cndmask_b32_e32 v90, 0, v90, vcc
	v_cndmask_b32_e32 v91, 0, v91, vcc
	v_cmp_lt_i32_e32 vcc, 7, v179
	s_nop 1
	v_cndmask_b32_e32 v92, 0, v92, vcc
	v_cndmask_b32_e32 v93, 0, v93, vcc
	v_cndmask_b32_e32 v94, 0, v94, vcc
	v_cndmask_b32_e32 v95, 0, v95, vcc
	v_cmp_lt_i32_e32 vcc, 6, v179
	s_nop 1
	v_cndmask_b32_e32 v96, 0, v96, vcc
	v_cndmask_b32_e32 v97, 0, v97, vcc
	v_cndmask_b32_e32 v98, 0, v98, vcc
	v_cndmask_b32_e32 v99, 0, v99, vcc
	v_cmp_lt_i32_e32 vcc, 5, v179
	s_nop 1
	v_cndmask_b32_e32 v100, 0, v100, vcc
	v_cndmask_b32_e32 v101, 0, v101, vcc
	v_cndmask_b32_e32 v102, 0, v102, vcc
	v_cndmask_b32_e32 v103, 0, v103, vcc
	v_cmp_lt_i32_e32 vcc, 4, v179
	s_nop 1
	v_cndmask_b32_e32 v104, 0, v104, vcc
	v_cndmask_b32_e32 v105, 0, v105, vcc
	v_cndmask_b32_e32 v106, 0, v106, vcc
	v_cndmask_b32_e32 v107, 0, v107, vcc
	v_cmp_lt_i32_e32 vcc, 3, v179
	s_nop 1
	v_cndmask_b32_e32 v108, 0, v108, vcc
	v_cndmask_b32_e32 v109, 0, v109, vcc
	v_cndmask_b32_e32 v110, 0, v110, vcc
	v_cndmask_b32_e32 v111, 0, v111, vcc
	v_cmp_lt_i32_e32 vcc, 2, v179
	s_nop 1
	v_cndmask_b32_e32 v112, 0, v112, vcc
	v_cndmask_b32_e32 v113, 0, v113, vcc
	v_cndmask_b32_e32 v114, 0, v114, vcc
	v_cndmask_b32_e32 v115, 0, v115, vcc
	v_cmp_lt_i32_e32 vcc, 1, v179
	s_nop 1
	v_cndmask_b32_e32 v116, 0, v116, vcc
	v_cndmask_b32_e32 v117, 0, v117, vcc
	v_cndmask_b32_e32 v118, 0, v118, vcc
	v_cndmask_b32_e32 v119, 0, v119, vcc
	v_cmp_lt_i32_e32 vcc, 0, v179
	s_nop 1
	v_cndmask_b32_e32 v120, 0, v120, vcc
	v_cndmask_b32_e32 v121, 0, v121, vcc
	v_cndmask_b32_e32 v122, 0, v122, vcc
	v_cndmask_b32_e32 v123, 0, v123, vcc
.Lw16p_nz:
	v_mov_b64_e32 v[182:183], 0
	v_mov_b64_e32 v[184:185], 0
	v_mov_b64_e32 v[186:187], 0
	v_mov_b64_e32 v[188:189], 0
	s_waitcnt vmcnt(22)
	v_lshlrev_b32_e32 v190, 16, v64
	v_and_b32_e32 v191, s41, v64
	v_lshlrev_b32_e32 v192, 16, v65
	v_and_b32_e32 v193, s41, v65
	v_lshlrev_b32_e32 v194, 16, v66
	v_and_b32_e32 v195, s41, v66
	v_lshlrev_b32_e32 v196, 16, v67
	v_and_b32_e32 v197, s41, v67
	v_pk_add_f32 v[182:183], v[182:183], v[190:191]
	v_pk_add_f32 v[184:185], v[184:185], v[192:193]
	v_pk_add_f32 v[186:187], v[186:187], v[194:195]
	v_pk_add_f32 v[188:189], v[188:189], v[196:197]
	s_waitcnt vmcnt(21)
	v_lshlrev_b32_e32 v190, 16, v68
	v_and_b32_e32 v191, s41, v68
	v_lshlrev_b32_e32 v192, 16, v69
	v_and_b32_e32 v193, s41, v69
	v_lshlrev_b32_e32 v194, 16, v70
	v_and_b32_e32 v195, s41, v70
	v_lshlrev_b32_e32 v196, 16, v71
	v_and_b32_e32 v197, s41, v71
	v_pk_add_f32 v[182:183], v[182:183], v[190:191]
	v_pk_add_f32 v[184:185], v[184:185], v[192:193]
	v_pk_add_f32 v[186:187], v[186:187], v[194:195]
	v_pk_add_f32 v[188:189], v[188:189], v[196:197]
	s_waitcnt vmcnt(20)
	v_lshlrev_b32_e32 v190, 16, v72
	v_and_b32_e32 v191, s41, v72
	v_lshlrev_b32_e32 v192, 16, v73
	v_and_b32_e32 v193, s41, v73
	v_lshlrev_b32_e32 v194, 16, v74
	v_and_b32_e32 v195, s41, v74
	v_lshlrev_b32_e32 v196, 16, v75
	v_and_b32_e32 v197, s41, v75
	v_pk_add_f32 v[182:183], v[182:183], v[190:191]
	v_pk_add_f32 v[184:185], v[184:185], v[192:193]
	v_pk_add_f32 v[186:187], v[186:187], v[194:195]
	v_pk_add_f32 v[188:189], v[188:189], v[196:197]
	s_waitcnt vmcnt(19)
	v_lshlrev_b32_e32 v190, 16, v76
	v_and_b32_e32 v191, s41, v76
	v_lshlrev_b32_e32 v192, 16, v77
	v_and_b32_e32 v193, s41, v77
	v_lshlrev_b32_e32 v194, 16, v78
	v_and_b32_e32 v195, s41, v78
	v_lshlrev_b32_e32 v196, 16, v79
	v_and_b32_e32 v197, s41, v79
	v_pk_add_f32 v[182:183], v[182:183], v[190:191]
	v_pk_add_f32 v[184:185], v[184:185], v[192:193]
	v_pk_add_f32 v[186:187], v[186:187], v[194:195]
	v_pk_add_f32 v[188:189], v[188:189], v[196:197]
	s_waitcnt vmcnt(18)
	v_lshlrev_b32_e32 v190, 16, v80
	v_and_b32_e32 v191, s41, v80
	v_lshlrev_b32_e32 v192, 16, v81
	v_and_b32_e32 v193, s41, v81
	v_lshlrev_b32_e32 v194, 16, v82
	v_and_b32_e32 v195, s41, v82
	v_lshlrev_b32_e32 v196, 16, v83
	v_and_b32_e32 v197, s41, v83
	v_pk_add_f32 v[182:183], v[182:183], v[190:191]
	v_pk_add_f32 v[184:185], v[184:185], v[192:193]
	v_pk_add_f32 v[186:187], v[186:187], v[194:195]
	v_pk_add_f32 v[188:189], v[188:189], v[196:197]
	s_waitcnt vmcnt(17)
	v_lshlrev_b32_e32 v190, 16, v84
	v_and_b32_e32 v191, s41, v84
	v_lshlrev_b32_e32 v192, 16, v85
	v_and_b32_e32 v193, s41, v85
	v_lshlrev_b32_e32 v194, 16, v86
	v_and_b32_e32 v195, s41, v86
	v_lshlrev_b32_e32 v196, 16, v87
	v_and_b32_e32 v197, s41, v87
	v_pk_add_f32 v[182:183], v[182:183], v[190:191]
	v_pk_add_f32 v[184:185], v[184:185], v[192:193]
	v_pk_add_f32 v[186:187], v[186:187], v[194:195]
	v_pk_add_f32 v[188:189], v[188:189], v[196:197]
	s_waitcnt vmcnt(16)
	v_lshlrev_b32_e32 v190, 16, v88
	v_and_b32_e32 v191, s41, v88
	v_lshlrev_b32_e32 v192, 16, v89
	v_and_b32_e32 v193, s41, v89
	v_lshlrev_b32_e32 v194, 16, v90
	v_and_b32_e32 v195, s41, v90
	v_lshlrev_b32_e32 v196, 16, v91
	v_and_b32_e32 v197, s41, v91
	v_pk_add_f32 v[182:183], v[182:183], v[190:191]
	v_pk_add_f32 v[184:185], v[184:185], v[192:193]
	v_pk_add_f32 v[186:187], v[186:187], v[194:195]
	v_pk_add_f32 v[188:189], v[188:189], v[196:197]
	s_waitcnt vmcnt(15)
	v_lshlrev_b32_e32 v190, 16, v92
	v_and_b32_e32 v191, s41, v92
	v_lshlrev_b32_e32 v192, 16, v93
	v_and_b32_e32 v193, s41, v93
	v_lshlrev_b32_e32 v194, 16, v94
	v_and_b32_e32 v195, s41, v94
	v_lshlrev_b32_e32 v196, 16, v95
	v_and_b32_e32 v197, s41, v95
	v_pk_add_f32 v[182:183], v[182:183], v[190:191]
	v_pk_add_f32 v[184:185], v[184:185], v[192:193]
	v_pk_add_f32 v[186:187], v[186:187], v[194:195]
	v_pk_add_f32 v[188:189], v[188:189], v[196:197]
	s_waitcnt vmcnt(14)
	v_lshlrev_b32_e32 v190, 16, v96
	v_and_b32_e32 v191, s41, v96
	v_lshlrev_b32_e32 v192, 16, v97
	v_and_b32_e32 v193, s41, v97
	v_lshlrev_b32_e32 v194, 16, v98
	v_and_b32_e32 v195, s41, v98
	v_lshlrev_b32_e32 v196, 16, v99
	v_and_b32_e32 v197, s41, v99
	v_pk_add_f32 v[182:183], v[182:183], v[190:191]
	v_pk_add_f32 v[184:185], v[184:185], v[192:193]
	v_pk_add_f32 v[186:187], v[186:187], v[194:195]
	v_pk_add_f32 v[188:189], v[188:189], v[196:197]
	s_waitcnt vmcnt(13)
	v_lshlrev_b32_e32 v190, 16, v100
	v_and_b32_e32 v191, s41, v100
	v_lshlrev_b32_e32 v192, 16, v101
	v_and_b32_e32 v193, s41, v101
	v_lshlrev_b32_e32 v194, 16, v102
	v_and_b32_e32 v195, s41, v102
	v_lshlrev_b32_e32 v196, 16, v103
	v_and_b32_e32 v197, s41, v103
	v_pk_add_f32 v[182:183], v[182:183], v[190:191]
	v_pk_add_f32 v[184:185], v[184:185], v[192:193]
	v_pk_add_f32 v[186:187], v[186:187], v[194:195]
	v_pk_add_f32 v[188:189], v[188:189], v[196:197]
	s_waitcnt vmcnt(12)
	v_lshlrev_b32_e32 v190, 16, v104
	v_and_b32_e32 v191, s41, v104
	v_lshlrev_b32_e32 v192, 16, v105
	v_and_b32_e32 v193, s41, v105
	v_lshlrev_b32_e32 v194, 16, v106
	v_and_b32_e32 v195, s41, v106
	v_lshlrev_b32_e32 v196, 16, v107
	v_and_b32_e32 v197, s41, v107
	v_pk_add_f32 v[182:183], v[182:183], v[190:191]
	v_pk_add_f32 v[184:185], v[184:185], v[192:193]
	v_pk_add_f32 v[186:187], v[186:187], v[194:195]
	v_pk_add_f32 v[188:189], v[188:189], v[196:197]
	s_waitcnt vmcnt(11)
	v_lshlrev_b32_e32 v190, 16, v108
	v_and_b32_e32 v191, s41, v108
	v_lshlrev_b32_e32 v192, 16, v109
	v_and_b32_e32 v193, s41, v109
	v_lshlrev_b32_e32 v194, 16, v110
	v_and_b32_e32 v195, s41, v110
	v_lshlrev_b32_e32 v196, 16, v111
	v_and_b32_e32 v197, s41, v111
	v_pk_add_f32 v[182:183], v[182:183], v[190:191]
	v_pk_add_f32 v[184:185], v[184:185], v[192:193]
	v_pk_add_f32 v[186:187], v[186:187], v[194:195]
	v_pk_add_f32 v[188:189], v[188:189], v[196:197]
	s_waitcnt vmcnt(10)
	v_lshlrev_b32_e32 v190, 16, v112
	v_and_b32_e32 v191, s41, v112
	v_lshlrev_b32_e32 v192, 16, v113
	v_and_b32_e32 v193, s41, v113
	v_lshlrev_b32_e32 v194, 16, v114
	v_and_b32_e32 v195, s41, v114
	v_lshlrev_b32_e32 v196, 16, v115
	v_and_b32_e32 v197, s41, v115
	v_pk_add_f32 v[182:183], v[182:183], v[190:191]
	v_pk_add_f32 v[184:185], v[184:185], v[192:193]
	v_pk_add_f32 v[186:187], v[186:187], v[194:195]
	v_pk_add_f32 v[188:189], v[188:189], v[196:197]
	s_waitcnt vmcnt(9)
	v_lshlrev_b32_e32 v190, 16, v116
	v_and_b32_e32 v191, s41, v116
	v_lshlrev_b32_e32 v192, 16, v117
	v_and_b32_e32 v193, s41, v117
	v_lshlrev_b32_e32 v194, 16, v118
	v_and_b32_e32 v195, s41, v118
	v_lshlrev_b32_e32 v196, 16, v119
	v_and_b32_e32 v197, s41, v119
	v_pk_add_f32 v[182:183], v[182:183], v[190:191]
	v_pk_add_f32 v[184:185], v[184:185], v[192:193]
	v_pk_add_f32 v[186:187], v[186:187], v[194:195]
	v_pk_add_f32 v[188:189], v[188:189], v[196:197]
	s_waitcnt vmcnt(8)
	v_lshlrev_b32_e32 v190, 16, v120
	v_and_b32_e32 v191, s41, v120
	v_lshlrev_b32_e32 v192, 16, v121
	v_and_b32_e32 v193, s41, v121
	v_lshlrev_b32_e32 v194, 16, v122
	v_and_b32_e32 v195, s41, v122
	v_lshlrev_b32_e32 v196, 16, v123
	v_and_b32_e32 v197, s41, v123
	v_pk_add_f32 v[182:183], v[182:183], v[190:191]
	v_pk_add_f32 v[184:185], v[184:185], v[192:193]
	v_pk_add_f32 v[186:187], v[186:187], v[194:195]
	v_pk_add_f32 v[188:189], v[188:189], v[196:197]
	v_min_i32_e32 v206, 15, v179
	v_add_u32_e32 v206, 1, v206
	v_cvt_f32_i32_e32 v206, v206
	v_rcp_iflag_f32_e32 v206, v206
	s_waitcnt vmcnt(7)
	v_lshlrev_b32_e32 v190, 16, v124
	v_and_b32_e32 v191, s41, v124
	v_lshlrev_b32_e32 v192, 16, v125
	v_and_b32_e32 v193, s41, v125
	v_lshlrev_b32_e32 v194, 16, v126
	v_and_b32_e32 v195, s41, v126
	v_lshlrev_b32_e32 v196, 16, v127
	v_and_b32_e32 v197, s41, v127
	v_pk_add_f32 v[182:183], v[182:183], v[190:191]
	v_pk_add_f32 v[184:185], v[184:185], v[192:193]
	v_pk_add_f32 v[186:187], v[186:187], v[194:195]
	v_pk_add_f32 v[188:189], v[188:189], v[196:197]
	v_pk_fma_f32 v[198:199], v[206:207], v[182:183], v[190:191] op_sel_hi:[0,1,1] neg_lo:[0,0,1] neg_hi:[0,0,1]
	v_pk_fma_f32 v[200:201], v[206:207], v[184:185], v[192:193] op_sel_hi:[0,1,1] neg_lo:[0,0,1] neg_hi:[0,0,1]
	v_pk_fma_f32 v[202:203], v[206:207], v[186:187], v[194:195] op_sel_hi:[0,1,1] neg_lo:[0,0,1] neg_hi:[0,0,1]
	v_pk_fma_f32 v[204:205], v[206:207], v[188:189], v[196:197] op_sel_hi:[0,1,1] neg_lo:[0,0,1] neg_hi:[0,0,1]
	v_cvt_pk_bf16_f32 v156, v198, v199
	v_cvt_pk_bf16_f32 v157, v200, v201
	v_cvt_pk_bf16_f32 v158, v202, v203
	v_cvt_pk_bf16_f32 v159, v204, v205
	ds_write_b128 v208, v[156:159]
	v_lshlrev_b32_e32 v190, 16, v64
	v_and_b32_e32 v191, s41, v64
	v_lshlrev_b32_e32 v192, 16, v65
	v_and_b32_e32 v193, s41, v65
	v_lshlrev_b32_e32 v194, 16, v66
	v_and_b32_e32 v195, s41, v66
	v_lshlrev_b32_e32 v196, 16, v67
	v_and_b32_e32 v197, s41, v67
	v_pk_add_f32 v[182:183], v[182:183], v[190:191] neg_lo:[0,1] neg_hi:[0,1]
	v_pk_add_f32 v[184:185], v[184:185], v[192:193] neg_lo:[0,1] neg_hi:[0,1]
	v_pk_add_f32 v[186:187], v[186:187], v[194:195] neg_lo:[0,1] neg_hi:[0,1]
	v_pk_add_f32 v[188:189], v[188:189], v[196:197] neg_lo:[0,1] neg_hi:[0,1]
	v_or_b32_e32 v206, 1, v179
	v_min_i32_e32 v206, 15, v206
	v_add_u32_e32 v206, 1, v206
	v_cvt_f32_i32_e32 v206, v206
	v_rcp_iflag_f32_e32 v206, v206
	s_waitcnt vmcnt(6)
	v_lshlrev_b32_e32 v190, 16, v128
	v_and_b32_e32 v191, s41, v128
	v_lshlrev_b32_e32 v192, 16, v129
	v_and_b32_e32 v193, s41, v129
	v_lshlrev_b32_e32 v194, 16, v130
	v_and_b32_e32 v195, s41, v130
	v_lshlrev_b32_e32 v196, 16, v131
	v_and_b32_e32 v197, s41, v131
	v_pk_add_f32 v[182:183], v[182:183], v[190:191]
	v_pk_add_f32 v[184:185], v[184:185], v[192:193]
	v_pk_add_f32 v[186:187], v[186:187], v[194:195]
	v_pk_add_f32 v[188:189], v[188:189], v[196:197]
	v_pk_fma_f32 v[198:199], v[206:207], v[182:183], v[190:191] op_sel_hi:[0,1,1] neg_lo:[0,0,1] neg_hi:[0,0,1]
	v_pk_fma_f32 v[200:201], v[206:207], v[184:185], v[192:193] op_sel_hi:[0,1,1] neg_lo:[0,0,1] neg_hi:[0,0,1]
	v_pk_fma_f32 v[202:203], v[206:207], v[186:187], v[194:195] op_sel_hi:[0,1,1] neg_lo:[0,0,1] neg_hi:[0,0,1]
	v_pk_fma_f32 v[204:205], v[206:207], v[188:189], v[196:197] op_sel_hi:[0,1,1] neg_lo:[0,0,1] neg_hi:[0,0,1]
	v_cvt_pk_bf16_f32 v156, v198, v199
	v_cvt_pk_bf16_f32 v157, v200, v201
	v_cvt_pk_bf16_f32 v158, v202, v203
	v_cvt_pk_bf16_f32 v159, v204, v205
	ds_write_b128 v208, v[156:159] offset:528
	v_lshlrev_b32_e32 v190, 16, v68
	v_and_b32_e32 v191, s41, v68
	v_lshlrev_b32_e32 v192, 16, v69
	v_and_b32_e32 v193, s41, v69
	v_lshlrev_b32_e32 v194, 16, v70
	v_and_b32_e32 v195, s41, v70
	v_lshlrev_b32_e32 v196, 16, v71
	v_and_b32_e32 v197, s41, v71
	v_pk_add_f32 v[182:183], v[182:183], v[190:191] neg_lo:[0,1] neg_hi:[0,1]
	v_pk_add_f32 v[184:185], v[184:185], v[192:193] neg_lo:[0,1] neg_hi:[0,1]
	v_pk_add_f32 v[186:187], v[186:187], v[194:195] neg_lo:[0,1] neg_hi:[0,1]
	v_pk_add_f32 v[188:189], v[188:189], v[196:197] neg_lo:[0,1] neg_hi:[0,1]
	v_or_b32_e32 v206, 2, v179
	v_min_i32_e32 v206, 15, v206
	v_add_u32_e32 v206, 1, v206
	v_cvt_f32_i32_e32 v206, v206
	v_rcp_iflag_f32_e32 v206, v206
	s_waitcnt vmcnt(5)
	v_lshlrev_b32_e32 v190, 16, v132
	v_and_b32_e32 v191, s41, v132
	v_lshlrev_b32_e32 v192, 16, v133
	v_and_b32_e32 v193, s41, v133
	v_lshlrev_b32_e32 v194, 16, v134
	v_and_b32_e32 v195, s41, v134
	v_lshlrev_b32_e32 v196, 16, v135
	v_and_b32_e32 v197, s41, v135
	v_pk_add_f32 v[182:183], v[182:183], v[190:191]
	v_pk_add_f32 v[184:185], v[184:185], v[192:193]
	v_pk_add_f32 v[186:187], v[186:187], v[194:195]
	v_pk_add_f32 v[188:189], v[188:189], v[196:197]
	v_pk_fma_f32 v[198:199], v[206:207], v[182:183], v[190:191] op_sel_hi:[0,1,1] neg_lo:[0,0,1] neg_hi:[0,0,1]
	v_pk_fma_f32 v[200:201], v[206:207], v[184:185], v[192:193] op_sel_hi:[0,1,1] neg_lo:[0,0,1] neg_hi:[0,0,1]
	v_pk_fma_f32 v[202:203], v[206:207], v[186:187], v[194:195] op_sel_hi:[0,1,1] neg_lo:[0,0,1] neg_hi:[0,0,1]
	v_pk_fma_f32 v[204:205], v[206:207], v[188:189], v[196:197] op_sel_hi:[0,1,1] neg_lo:[0,0,1] neg_hi:[0,0,1]
	v_cvt_pk_bf16_f32 v156, v198, v199
	v_cvt_pk_bf16_f32 v157, v200, v201
	v_cvt_pk_bf16_f32 v158, v202, v203
	v_cvt_pk_bf16_f32 v159, v204, v205
	ds_write_b128 v208, v[156:159] offset:1056
	v_lshlrev_b32_e32 v190, 16, v72
	v_and_b32_e32 v191, s41, v72
	v_lshlrev_b32_e32 v192, 16, v73
	v_and_b32_e32 v193, s41, v73
	v_lshlrev_b32_e32 v194, 16, v74
	v_and_b32_e32 v195, s41, v74
	v_lshlrev_b32_e32 v196, 16, v75
	v_and_b32_e32 v197, s41, v75
	v_pk_add_f32 v[182:183], v[182:183], v[190:191] neg_lo:[0,1] neg_hi:[0,1]
	v_pk_add_f32 v[184:185], v[184:185], v[192:193] neg_lo:[0,1] neg_hi:[0,1]
	v_pk_add_f32 v[186:187], v[186:187], v[194:195] neg_lo:[0,1] neg_hi:[0,1]
	v_pk_add_f32 v[188:189], v[188:189], v[196:197] neg_lo:[0,1] neg_hi:[0,1]
	v_or_b32_e32 v206, 3, v179
	v_min_i32_e32 v206, 15, v206
	v_add_u32_e32 v206, 1, v206
	v_cvt_f32_i32_e32 v206, v206
	v_rcp_iflag_f32_e32 v206, v206
	s_waitcnt vmcnt(4)
	v_lshlrev_b32_e32 v190, 16, v136
	v_and_b32_e32 v191, s41, v136
	v_lshlrev_b32_e32 v192, 16, v137
	v_and_b32_e32 v193, s41, v137
	v_lshlrev_b32_e32 v194, 16, v138
	v_and_b32_e32 v195, s41, v138
	v_lshlrev_b32_e32 v196, 16, v139
	v_and_b32_e32 v197, s41, v139
	v_pk_add_f32 v[182:183], v[182:183], v[190:191]
	v_pk_add_f32 v[184:185], v[184:185], v[192:193]
	v_pk_add_f32 v[186:187], v[186:187], v[194:195]
	v_pk_add_f32 v[188:189], v[188:189], v[196:197]
	v_pk_fma_f32 v[198:199], v[206:207], v[182:183], v[190:191] op_sel_hi:[0,1,1] neg_lo:[0,0,1] neg_hi:[0,0,1]
	v_pk_fma_f32 v[200:201], v[206:207], v[184:185], v[192:193] op_sel_hi:[0,1,1] neg_lo:[0,0,1] neg_hi:[0,0,1]
	v_pk_fma_f32 v[202:203], v[206:207], v[186:187], v[194:195] op_sel_hi:[0,1,1] neg_lo:[0,0,1] neg_hi:[0,0,1]
	v_pk_fma_f32 v[204:205], v[206:207], v[188:189], v[196:197] op_sel_hi:[0,1,1] neg_lo:[0,0,1] neg_hi:[0,0,1]
	v_cvt_pk_bf16_f32 v156, v198, v199
	v_cvt_pk_bf16_f32 v157, v200, v201
	v_cvt_pk_bf16_f32 v158, v202, v203
	v_cvt_pk_bf16_f32 v159, v204, v205
	ds_write_b128 v208, v[156:159] offset:1584
	v_lshlrev_b32_e32 v190, 16, v76
	v_and_b32_e32 v191, s41, v76
	v_lshlrev_b32_e32 v192, 16, v77
	v_and_b32_e32 v193, s41, v77
	v_lshlrev_b32_e32 v194, 16, v78
	v_and_b32_e32 v195, s41, v78
	v_lshlrev_b32_e32 v196, 16, v79
	v_and_b32_e32 v197, s41, v79
	v_pk_add_f32 v[182:183], v[182:183], v[190:191] neg_lo:[0,1] neg_hi:[0,1]
	v_pk_add_f32 v[184:185], v[184:185], v[192:193] neg_lo:[0,1] neg_hi:[0,1]
	v_pk_add_f32 v[186:187], v[186:187], v[194:195] neg_lo:[0,1] neg_hi:[0,1]
	v_pk_add_f32 v[188:189], v[188:189], v[196:197] neg_lo:[0,1] neg_hi:[0,1]
	v_or_b32_e32 v206, 4, v179
	v_min_i32_e32 v206, 15, v206
	v_add_u32_e32 v206, 1, v206
	v_cvt_f32_i32_e32 v206, v206
	v_rcp_iflag_f32_e32 v206, v206
	s_waitcnt vmcnt(3)
	v_lshlrev_b32_e32 v190, 16, v140
	v_and_b32_e32 v191, s41, v140
	v_lshlrev_b32_e32 v192, 16, v141
	v_and_b32_e32 v193, s41, v141
	v_lshlrev_b32_e32 v194, 16, v142
	v_and_b32_e32 v195, s41, v142
	v_lshlrev_b32_e32 v196, 16, v143
	v_and_b32_e32 v197, s41, v143
	v_pk_add_f32 v[182:183], v[182:183], v[190:191]
	v_pk_add_f32 v[184:185], v[184:185], v[192:193]
	v_pk_add_f32 v[186:187], v[186:187], v[194:195]
	v_pk_add_f32 v[188:189], v[188:189], v[196:197]
	v_pk_fma_f32 v[198:199], v[206:207], v[182:183], v[190:191] op_sel_hi:[0,1,1] neg_lo:[0,0,1] neg_hi:[0,0,1]
	v_pk_fma_f32 v[200:201], v[206:207], v[184:185], v[192:193] op_sel_hi:[0,1,1] neg_lo:[0,0,1] neg_hi:[0,0,1]
	v_pk_fma_f32 v[202:203], v[206:207], v[186:187], v[194:195] op_sel_hi:[0,1,1] neg_lo:[0,0,1] neg_hi:[0,0,1]
	v_pk_fma_f32 v[204:205], v[206:207], v[188:189], v[196:197] op_sel_hi:[0,1,1] neg_lo:[0,0,1] neg_hi:[0,0,1]
	v_cvt_pk_bf16_f32 v156, v198, v199
	v_cvt_pk_bf16_f32 v157, v200, v201
	v_cvt_pk_bf16_f32 v158, v202, v203
	v_cvt_pk_bf16_f32 v159, v204, v205
	ds_write_b128 v208, v[156:159] offset:2112
	v_lshlrev_b32_e32 v190, 16, v80
	v_and_b32_e32 v191, s41, v80
	v_lshlrev_b32_e32 v192, 16, v81
	v_and_b32_e32 v193, s41, v81
	v_lshlrev_b32_e32 v194, 16, v82
	v_and_b32_e32 v195, s41, v82
	v_lshlrev_b32_e32 v196, 16, v83
	v_and_b32_e32 v197, s41, v83
	v_pk_add_f32 v[182:183], v[182:183], v[190:191] neg_lo:[0,1] neg_hi:[0,1]
	v_pk_add_f32 v[184:185], v[184:185], v[192:193] neg_lo:[0,1] neg_hi:[0,1]
	v_pk_add_f32 v[186:187], v[186:187], v[194:195] neg_lo:[0,1] neg_hi:[0,1]
	v_pk_add_f32 v[188:189], v[188:189], v[196:197] neg_lo:[0,1] neg_hi:[0,1]
	v_or_b32_e32 v206, 5, v179
	v_min_i32_e32 v206, 15, v206
	v_add_u32_e32 v206, 1, v206
	v_cvt_f32_i32_e32 v206, v206
	v_rcp_iflag_f32_e32 v206, v206
	s_waitcnt vmcnt(2)
	v_lshlrev_b32_e32 v190, 16, v144
	v_and_b32_e32 v191, s41, v144
	v_lshlrev_b32_e32 v192, 16, v145
	v_and_b32_e32 v193, s41, v145
	v_lshlrev_b32_e32 v194, 16, v146
	v_and_b32_e32 v195, s41, v146
	v_lshlrev_b32_e32 v196, 16, v147
	v_and_b32_e32 v197, s41, v147
	v_pk_add_f32 v[182:183], v[182:183], v[190:191]
	v_pk_add_f32 v[184:185], v[184:185], v[192:193]
	v_pk_add_f32 v[186:187], v[186:187], v[194:195]
	v_pk_add_f32 v[188:189], v[188:189], v[196:197]
	v_pk_fma_f32 v[198:199], v[206:207], v[182:183], v[190:191] op_sel_hi:[0,1,1] neg_lo:[0,0,1] neg_hi:[0,0,1]
	v_pk_fma_f32 v[200:201], v[206:207], v[184:185], v[192:193] op_sel_hi:[0,1,1] neg_lo:[0,0,1] neg_hi:[0,0,1]
	v_pk_fma_f32 v[202:203], v[206:207], v[186:187], v[194:195] op_sel_hi:[0,1,1] neg_lo:[0,0,1] neg_hi:[0,0,1]
	v_pk_fma_f32 v[204:205], v[206:207], v[188:189], v[196:197] op_sel_hi:[0,1,1] neg_lo:[0,0,1] neg_hi:[0,0,1]
	v_cvt_pk_bf16_f32 v156, v198, v199
	v_cvt_pk_bf16_f32 v157, v200, v201
	v_cvt_pk_bf16_f32 v158, v202, v203
	v_cvt_pk_bf16_f32 v159, v204, v205
	ds_write_b128 v208, v[156:159] offset:2640
	v_lshlrev_b32_e32 v190, 16, v84
	v_and_b32_e32 v191, s41, v84
	v_lshlrev_b32_e32 v192, 16, v85
	v_and_b32_e32 v193, s41, v85
	v_lshlrev_b32_e32 v194, 16, v86
	v_and_b32_e32 v195, s41, v86
	v_lshlrev_b32_e32 v196, 16, v87
	v_and_b32_e32 v197, s41, v87
	v_pk_add_f32 v[182:183], v[182:183], v[190:191] neg_lo:[0,1] neg_hi:[0,1]
	v_pk_add_f32 v[184:185], v[184:185], v[192:193] neg_lo:[0,1] neg_hi:[0,1]
	v_pk_add_f32 v[186:187], v[186:187], v[194:195] neg_lo:[0,1] neg_hi:[0,1]
	v_pk_add_f32 v[188:189], v[188:189], v[196:197] neg_lo:[0,1] neg_hi:[0,1]
	v_or_b32_e32 v206, 6, v179
	v_min_i32_e32 v206, 15, v206
	v_add_u32_e32 v206, 1, v206
	v_cvt_f32_i32_e32 v206, v206
	v_rcp_iflag_f32_e32 v206, v206
	s_waitcnt vmcnt(1)
	v_lshlrev_b32_e32 v190, 16, v148
	v_and_b32_e32 v191, s41, v148
	v_lshlrev_b32_e32 v192, 16, v149
	v_and_b32_e32 v193, s41, v149
	v_lshlrev_b32_e32 v194, 16, v150
	v_and_b32_e32 v195, s41, v150
	v_lshlrev_b32_e32 v196, 16, v151
	v_and_b32_e32 v197, s41, v151
	v_pk_add_f32 v[182:183], v[182:183], v[190:191]
	v_pk_add_f32 v[184:185], v[184:185], v[192:193]
	v_pk_add_f32 v[186:187], v[186:187], v[194:195]
	v_pk_add_f32 v[188:189], v[188:189], v[196:197]
	v_pk_fma_f32 v[198:199], v[206:207], v[182:183], v[190:191] op_sel_hi:[0,1,1] neg_lo:[0,0,1] neg_hi:[0,0,1]
	v_pk_fma_f32 v[200:201], v[206:207], v[184:185], v[192:193] op_sel_hi:[0,1,1] neg_lo:[0,0,1] neg_hi:[0,0,1]
	v_pk_fma_f32 v[202:203], v[206:207], v[186:187], v[194:195] op_sel_hi:[0,1,1] neg_lo:[0,0,1] neg_hi:[0,0,1]
	v_pk_fma_f32 v[204:205], v[206:207], v[188:189], v[196:197] op_sel_hi:[0,1,1] neg_lo:[0,0,1] neg_hi:[0,0,1]
	v_cvt_pk_bf16_f32 v156, v198, v199
	v_cvt_pk_bf16_f32 v157, v200, v201
	v_cvt_pk_bf16_f32 v158, v202, v203
	v_cvt_pk_bf16_f32 v159, v204, v205
	ds_write_b128 v208, v[156:159] offset:3168
	v_lshlrev_b32_e32 v190, 16, v88
	v_and_b32_e32 v191, s41, v88
	v_lshlrev_b32_e32 v192, 16, v89
	v_and_b32_e32 v193, s41, v89
	v_lshlrev_b32_e32 v194, 16, v90
	v_and_b32_e32 v195, s41, v90
	v_lshlrev_b32_e32 v196, 16, v91
	v_and_b32_e32 v197, s41, v91
	v_pk_add_f32 v[182:183], v[182:183], v[190:191] neg_lo:[0,1] neg_hi:[0,1]
	v_pk_add_f32 v[184:185], v[184:185], v[192:193] neg_lo:[0,1] neg_hi:[0,1]
	v_pk_add_f32 v[186:187], v[186:187], v[194:195] neg_lo:[0,1] neg_hi:[0,1]
	v_pk_add_f32 v[188:189], v[188:189], v[196:197] neg_lo:[0,1] neg_hi:[0,1]
	v_or_b32_e32 v206, 7, v179
	v_min_i32_e32 v206, 15, v206
	v_add_u32_e32 v206, 1, v206
	v_cvt_f32_i32_e32 v206, v206
	v_rcp_iflag_f32_e32 v206, v206
	s_waitcnt vmcnt(0)
	v_lshlrev_b32_e32 v190, 16, v152
	v_and_b32_e32 v191, s41, v152
	v_lshlrev_b32_e32 v192, 16, v153
	v_and_b32_e32 v193, s41, v153
	v_lshlrev_b32_e32 v194, 16, v154
	v_and_b32_e32 v195, s41, v154
	v_lshlrev_b32_e32 v196, 16, v155
	v_and_b32_e32 v197, s41, v155
	v_pk_add_f32 v[182:183], v[182:183], v[190:191]
	v_pk_add_f32 v[184:185], v[184:185], v[192:193]
	v_pk_add_f32 v[186:187], v[186:187], v[194:195]
	v_pk_add_f32 v[188:189], v[188:189], v[196:197]
	v_pk_fma_f32 v[198:199], v[206:207], v[182:183], v[190:191] op_sel_hi:[0,1,1] neg_lo:[0,0,1] neg_hi:[0,0,1]
	v_pk_fma_f32 v[200:201], v[206:207], v[184:185], v[192:193] op_sel_hi:[0,1,1] neg_lo:[0,0,1] neg_hi:[0,0,1]
	v_pk_fma_f32 v[202:203], v[206:207], v[186:187], v[194:195] op_sel_hi:[0,1,1] neg_lo:[0,0,1] neg_hi:[0,0,1]
	v_pk_fma_f32 v[204:205], v[206:207], v[188:189], v[196:197] op_sel_hi:[0,1,1] neg_lo:[0,0,1] neg_hi:[0,0,1]
	v_cvt_pk_bf16_f32 v64, v198, v199
	v_cvt_pk_bf16_f32 v65, v200, v201
	v_cvt_pk_bf16_f32 v66, v202, v203
	v_cvt_pk_bf16_f32 v67, v204, v205
	s_mov_b64 s[16:17], 0
